# quad-coalesced lane layout also for the key / value^T up-projection and split-K partial epilogues
# speedup vs baseline: 1.0247x; 1.0041x over previous
; #define TID() tid_now(wv)
; DEVI const float* IN(int i) { return *(const float* const __attribute__((address_space(4)))*)(kargs() + 8 * i); }
; DEVI float* OUTP() { return *(float* const __attribute__((address_space(4)))*)(kargs() + 8 * 21); }
; DEVI unsigned char* WSP() { return *(unsigned char* const __attribute__((address_space(4)))*)(kargs() + 8 * 22); }
; template <class Epi, class Sched>
; __device__ __forceinline__ void gemm_phase(int wv, LAS unsigned char* lds, const Gemm g, const Sched& S, const Epi& E) {
;     ...
;         { const int t2 = TID(), w2 = __builtin_amdgcn_readfirstlane(t2 >> 6), l2 = t2 & 63; Unit eu = cur; eu.ks = 0; if (g.nNr) { eu.pn = cur.pn % g.nNr; eu.ks = cur.pn / g.nNr; } E(acc, eu, w2 >> 2, w2 & 3, l2 & 15, l2 >> 4); }
;     DEVI void operator()(AccRef acc, const Unit& u, int wr, int wc, int fr, int fq) const {
;         unsigned char* ws = WSP(); const float* gk = IN(12) + l * 96;
;         const float* krc = cache ? IN(3) + (size_t)l * MC * 32 : OUTP();
;         const float* ssq_zkv = (const float*)(ws + O_SSQZ) + (size_t)(5 + l) * MT;
;         const int hd = 4 * u.pn + wc;
;         const bool samp = !cache && (u.pm * 256 >= MP);
;         bf16_t* kbase = (bf16_t*)(ws + ((cache || samp) ? O_KS : O_KP));
; #pragma unroll
;         for (int ai = 0; ai < 2; ++ai) {
;             f32x4 k0[4], k1[4]; float rr[4]; unsigned ko[4];
; #pragma unroll
;             for (int m = 0; m < 4; ++m) {
;                 const int row = ROWOF(u);
;                 const float* krp;
;                 if (cache) { krp = krc + (size_t)row * 32; ko[m] = ((unsigned)((row >> 12) * 8 + hd) * KSL + (row & 4095)) * 96u; rr[m] = 1.f; }
;                 else {
;                     rr[m] = ssq_zkv[row];
;                     if (!samp) { krp = krc + OUT_KRP + ((size_t)l * MP + row) * 32; ko[m] = ((unsigned)((row >> 12) * 8 + hd) * 4096u + (row & 4095)) * 96u; }
;                     else { const int rw = row - MP; krp = krc + OUT_KRS + ((size_t)l * MS + rw) * 32; ko[m] = ((unsigned)((rw >> 4) * 8 + hd) * KSL + 4096u + (rw & 15)) * 96u; }
;                 }
;                 k0[m] = *(const f32x4*)(krp + 8 * fq); k1[m] = *(const f32x4*)(krp + 8 * fq + 4);
.LBB0_911:
	s_mov_b64 s[66:67], s[0:1]
	v_mbcnt_lo_u32_b32 v0, -1, 0
	v_mbcnt_hi_u32_b32 v0, -1, v0
	v_lshl_or_b32 v0, s33, 6, v0
	v_bfe_u32 v209, v0, 2, 4
	v_and_b32_e32 v207, 3, v0
	v_lshl_add_u32 v207, v207, 4, v209
	v_lshlrev_b32_e32 v207, 2, v207
	ds_bpermute_b32 v2, v207, v2
	ds_bpermute_b32 v3, v207, v3
	ds_bpermute_b32 v4, v207, v4
	ds_bpermute_b32 v5, v207, v5
	ds_bpermute_b32 v6, v207, v6
	ds_bpermute_b32 v7, v207, v7
	ds_bpermute_b32 v8, v207, v8
	ds_bpermute_b32 v9, v207, v9
	s_waitcnt lgkmcnt(7)
	ds_bpermute_b32 v10, v207, v10
	ds_bpermute_b32 v11, v207, v11
	ds_bpermute_b32 v12, v207, v12
	ds_bpermute_b32 v13, v207, v13
	ds_bpermute_b32 v14, v207, v14
	ds_bpermute_b32 v15, v207, v15
	ds_bpermute_b32 v16, v207, v16
	ds_bpermute_b32 v17, v207, v17
	s_waitcnt lgkmcnt(7)
	ds_bpermute_b32 v18, v207, v18
	ds_bpermute_b32 v19, v207, v19
	ds_bpermute_b32 v20, v207, v20
	ds_bpermute_b32 v21, v207, v21
	ds_bpermute_b32 v22, v207, v22
	ds_bpermute_b32 v23, v207, v23
	ds_bpermute_b32 v24, v207, v24
	ds_bpermute_b32 v25, v207, v25
	s_waitcnt lgkmcnt(7)
	ds_bpermute_b32 v26, v207, v26
	ds_bpermute_b32 v27, v207, v27
	ds_bpermute_b32 v28, v207, v28
	ds_bpermute_b32 v29, v207, v29
	ds_bpermute_b32 v30, v207, v30
	ds_bpermute_b32 v31, v207, v31
	ds_bpermute_b32 v32, v207, v32
	ds_bpermute_b32 v33, v207, v33
	s_waitcnt lgkmcnt(7)
	ds_bpermute_b32 v34, v207, v34
	ds_bpermute_b32 v35, v207, v35
	ds_bpermute_b32 v36, v207, v36
	ds_bpermute_b32 v37, v207, v37
	ds_bpermute_b32 v38, v207, v38
	ds_bpermute_b32 v39, v207, v39
	ds_bpermute_b32 v40, v207, v40
	ds_bpermute_b32 v41, v207, v41
	s_waitcnt lgkmcnt(7)
	ds_bpermute_b32 v42, v207, v42
	ds_bpermute_b32 v43, v207, v43
	ds_bpermute_b32 v44, v207, v44
	ds_bpermute_b32 v45, v207, v45
	ds_bpermute_b32 v46, v207, v46
	ds_bpermute_b32 v47, v207, v47
	ds_bpermute_b32 v48, v207, v48
	ds_bpermute_b32 v49, v207, v49
	s_waitcnt lgkmcnt(7)
	ds_bpermute_b32 v50, v207, v50
	ds_bpermute_b32 v51, v207, v51
	ds_bpermute_b32 v52, v207, v52
	ds_bpermute_b32 v53, v207, v53
	ds_bpermute_b32 v54, v207, v54
	ds_bpermute_b32 v55, v207, v55
	ds_bpermute_b32 v56, v207, v56
	ds_bpermute_b32 v57, v207, v57
	s_waitcnt lgkmcnt(7)
	ds_bpermute_b32 v58, v207, v58
	ds_bpermute_b32 v59, v207, v59
	ds_bpermute_b32 v60, v207, v60
	ds_bpermute_b32 v61, v207, v61
	ds_bpermute_b32 v62, v207, v62
	ds_bpermute_b32 v63, v207, v63
	ds_bpermute_b32 v64, v207, v64
	ds_bpermute_b32 v65, v207, v65
	s_waitcnt lgkmcnt(7)
	ds_bpermute_b32 v66, v207, v66
	ds_bpermute_b32 v67, v207, v67
	ds_bpermute_b32 v68, v207, v68
	ds_bpermute_b32 v69, v207, v69
	ds_bpermute_b32 v70, v207, v70
	ds_bpermute_b32 v71, v207, v71
	ds_bpermute_b32 v72, v207, v72
	ds_bpermute_b32 v73, v207, v73
	s_waitcnt lgkmcnt(7)
	ds_bpermute_b32 v74, v207, v74
	ds_bpermute_b32 v75, v207, v75
	ds_bpermute_b32 v76, v207, v76
	ds_bpermute_b32 v77, v207, v77
	ds_bpermute_b32 v78, v207, v78
	ds_bpermute_b32 v79, v207, v79
	ds_bpermute_b32 v80, v207, v80
	ds_bpermute_b32 v81, v207, v81
	s_waitcnt lgkmcnt(7)
	ds_bpermute_b32 v82, v207, v82
	ds_bpermute_b32 v83, v207, v83
	ds_bpermute_b32 v84, v207, v84
	ds_bpermute_b32 v85, v207, v85
	ds_bpermute_b32 v86, v207, v86
	ds_bpermute_b32 v87, v207, v87
	ds_bpermute_b32 v88, v207, v88
	ds_bpermute_b32 v89, v207, v89
	s_waitcnt lgkmcnt(7)
	ds_bpermute_b32 v90, v207, v90
	ds_bpermute_b32 v91, v207, v91
	ds_bpermute_b32 v92, v207, v92
	ds_bpermute_b32 v93, v207, v93
	ds_bpermute_b32 v94, v207, v94
	ds_bpermute_b32 v95, v207, v95
	ds_bpermute_b32 v96, v207, v96
	ds_bpermute_b32 v97, v207, v97
	s_waitcnt lgkmcnt(7)
	ds_bpermute_b32 v126, v207, v126
	ds_bpermute_b32 v127, v207, v127
	ds_bpermute_b32 v128, v207, v128
	ds_bpermute_b32 v129, v207, v129
	ds_bpermute_b32 v130, v207, v130
	ds_bpermute_b32 v131, v207, v131
	ds_bpermute_b32 v132, v207, v132
	ds_bpermute_b32 v133, v207, v133
	s_waitcnt lgkmcnt(7)
	ds_bpermute_b32 v138, v207, v138
	ds_bpermute_b32 v139, v207, v139
	ds_bpermute_b32 v140, v207, v140
	ds_bpermute_b32 v141, v207, v141
	ds_bpermute_b32 v142, v207, v142
	ds_bpermute_b32 v143, v207, v143
	ds_bpermute_b32 v144, v207, v144
	ds_bpermute_b32 v145, v207, v145
	s_waitcnt lgkmcnt(7)
	ds_bpermute_b32 v154, v207, v154
	ds_bpermute_b32 v155, v207, v155
	ds_bpermute_b32 v156, v207, v156
	ds_bpermute_b32 v157, v207, v157
	ds_bpermute_b32 v158, v207, v158
	ds_bpermute_b32 v159, v207, v159
	ds_bpermute_b32 v160, v207, v160
	ds_bpermute_b32 v161, v207, v161
	s_waitcnt lgkmcnt(7)
	ds_bpermute_b32 v170, v207, v170
	ds_bpermute_b32 v171, v207, v171
	ds_bpermute_b32 v172, v207, v172
	ds_bpermute_b32 v173, v207, v173
	ds_bpermute_b32 v174, v207, v174
	ds_bpermute_b32 v175, v207, v175
	ds_bpermute_b32 v176, v207, v176
	ds_bpermute_b32 v177, v207, v177
	s_waitcnt lgkmcnt(0)
	s_load_dwordx2 s[74:75], s[66:67], 0xb0
	v_readfirstlane_b32 s5, v0
	s_bfe_u32 s47, s5, 0x20006
	s_mov_b64 s[66:67], s[0:1]
	s_waitcnt lgkmcnt(0)
	s_add_u32 s57, s74, s43
	s_addc_u32 s59, s75, 0
	s_load_dwordx2 s[72:73], s[66:67], 0x60
	s_add_u32 s66, s57, 0x147800
	s_addc_u32 s67, s59, 0
	s_lshl_b32 s57, s64, 2
	s_or_b32 s47, s47, s57
	s_cmpk_gt_i32 s4, 0x7f
	s_cselect_b64 s[64:65], -1, 0
	s_cmpk_lt_i32 s4, 0x80
	s_cselect_b64 s[76:77], -1, 0
	s_ashr_i32 s5, s5, 2
	s_lshl_b32 s4, s4, 8
	s_and_b32 s57, s5, 0xffffffc0
	v_bfe_u32 v207, v0, 2, 4
	s_add_i32 s57, s57, s4
	v_or_b32_e32 v106, s57, v207
	v_ashrrev_i32_e32 v107, 31, v106
	s_mov_b64 s[68:69], s[0:1]
	v_lshl_add_u64 v[98:99], v[106:107], 2, s[66:67]
	global_load_dword v116, v[98:99], off
	s_load_dwordx2 s[4:5], s[68:69], 0xa8
	s_waitcnt lgkmcnt(0)
	s_add_u32 s59, s4, s10
	s_addc_u32 s68, s5, s11
	s_add_u32 s70, s59, 0xc200000
	s_addc_u32 s71, s68, 0
	s_lshr_b32 s59, s57, 9
	s_and_b32 s59, s59, 0xffff8
	s_add_i32 s59, s59, s47
	s_lshl_b32 s59, s59, 12
	s_add_u32 s4, s4, s50
	s_addc_u32 s5, s5, s51
	s_add_u32 s68, s4, 0xcb78000
	s_addc_u32 s69, s5, 0
	s_mov_b64 s[4:5], -1
	s_and_b64 vcc, exec, s[64:65]
	s_cbranch_vccnz .LBB0_913
	v_lshlrev_b64 v[98:99], 7, v[106:107]
	v_and_b32_e32 v100, 0xfcf, v106
	v_lshl_add_u64 v[98:99], s[70:71], 0, v[98:99]
	v_or_b32_e32 v108, s59, v100
	s_mov_b64 s[4:5], 0

;     DEVI void operator()(AccRef acc, const Unit& u, int wr, int wc, int fr, int fq) const {
;     ...
;                 const int row = ROWOF(u);
;                 const float* krp;
;                 if (cache) { krp = krc + (size_t)row * 32; ko[m] = ((unsigned)((row >> 12) * 8 + hd) * KSL + (row & 4095)) * 96u; rr[m] = 1.f; }
;                 else {
;                     rr[m] = ssq_zkv[row];
;                     if (!samp) { krp = krc + OUT_KRP + ((size_t)l * MP + row) * 32; ko[m] = ((unsigned)((row >> 12) * 8 + hd) * 4096u + (row & 4095)) * 96u; }
;                     else { const int rw = row - MP; krp = krc + OUT_KRS + ((size_t)l * MS + rw) * 32; ko[m] = ((unsigned)((rw >> 4) * 8 + hd) * KSL + 4096u + (rw & 15)) * 96u; }
;                 }
;                 k0[m] = *(const f32x4*)(krp + 8 * fq); k1[m] = *(const f32x4*)(krp + 8 * fq + 4);
.LBB0_915:
	v_lshlrev_b32_e32 v0, 3, v0
	v_and_b32_e32 v209, 24, v0
	v_lshlrev_b32_e32 v0, 2, v209
	v_or_b32_e32 v100, 16, v106
	v_lshl_add_u64 v[98:99], v[98:99], 0, v[0:1]
	v_ashrrev_i32_e32 v101, 31, v100
	global_load_dwordx4 v[162:165], v[98:99], off offset:16
	global_load_dwordx4 v[166:169], v[98:99], off
	v_lshl_add_u64 v[98:99], v[100:101], 2, s[66:67]
	global_load_dword v191, v[98:99], off
	v_cndmask_b32_e64 v98, 0, 1, s[76:77]
	v_cmp_ne_u32_e64 s[4:5], 1, v98
	s_andn2_b64 vcc, exec, s[76:77]
	s_mov_b64 s[76:77], -1
	s_cbranch_vccnz .LBB0_917
	v_lshlrev_b64 v[98:99], 7, v[100:101]
	v_and_b32_e32 v100, 0xfdf, v100
	v_lshl_add_u64 v[98:99], s[70:71], 0, v[98:99]
	v_or_b32_e32 v110, s59, v100
	s_mov_b64 s[76:77], 0

; DEVI u32x4 pack8(const f32x4 a, const f32x4 b) { u32x4 w; w.x = cvtpk(a[0], a[1]); w.y = cvtpk(a[2], a[3]); w.z = cvtpk(b[0], b[1]); w.w = cvtpk(b[2], b[3]); return w; }
; DEVI float ss4(const f32x4 a) { return (a[0] * a[0] + a[1] * a[1]) + (a[2] * a[2] + a[3] * a[3]); }
; DEVI float red_fq(float s) { s += __shfl_xor(s, 16); s += __shfl_xor(s, 32); return s; }
;     DEVI void operator()(AccRef acc, const Unit& u, int wr, int wc, int fr, int fq) const {
;     ...
;             const f32x4 g0 = *(const f32x4*)(gk + 8 * fq), g1 = *(const f32x4*)(gk + 8 * fq + 4), g2 = *(const f32x4*)(gk + 32 + 8 * fq), g3 = *(const f32x4*)(gk + 36 + 8 * fq),
;                         g4 = *(const f32x4*)(gk + 64 + 8 * fq), g5 = *(const f32x4*)(gk + 68 + 8 * fq);
; #pragma unroll
;             for (int m = 0; m < 4; ++m) {
;                 const float r = cache ? 1.f : rsqrtf(rr[m] * (1.f / 256.f) + EPSF);
;                 const f32x4 v00 = acc[ai][0][m][0] * r, v01 = acc[ai][0][m][1] * r, v10 = acc[ai][1][m][0] * r, v11 = acc[ai][1][m][1] * r;
;                 const float s = red_fq(((ss4(v00) + ss4(v01)) + (ss4(v10) + ss4(v11))) + (ss4(k0[m]) + ss4(k1[m])));
;                 const float sc = rsqrtf(s * (1.f / 96.f) + EPSF);
;                 bf16_t* kd = kbase + ko[m];
;                 *(u32x4*)(kd + 8 * fq) = pack8(v00 * (g0 * sc), v01 * (g1 * sc));
;                 *(u32x4*)(kd + 32 + 8 * fq) = pack8(v10 * (g2 * sc), v11 * (g3 * sc));
;                 *(u32x4*)(kd + 64 + 8 * fq) = pack8(k0[m] * (g4 * sc), k1[m] * (g5 * sc));
.LBB0_927:
	s_add_u32 s72, s72, s54
	s_addc_u32 s73, s73, s55
	v_and_b32_e32 v107, 64, v238
	v_xor_b32_e32 v106, 1, v238
	v_add_u32_e32 v195, 64, v107
	global_load_dwordx4 v[122:125], v0, s[72:73] offset:16
	global_load_dwordx4 v[134:137], v0, s[72:73]
	v_cmp_lt_i32_e32 vcc, v106, v195
	v_mul_lo_u32 v188, v112, s21
	v_mul_lo_u32 v190, v110, s21
	v_cndmask_b32_e32 v106, v238, v106, vcc
	v_lshlrev_b32_e32 v205, 2, v106
	s_waitcnt vmcnt(0)
	v_fmamk_f32 v106, v116, 0x3b800000, v233
	v_mul_f32_e32 v107, 0x4b800000, v106
	v_cmp_gt_f32_e32 vcc, s25, v106
	v_mul_lo_u32 v194, v108, s21
	s_and_b64 s[64:65], exec, s[64:65]
	v_cndmask_b32_e32 v106, v106, v107, vcc
	v_rsq_f32_e32 v196, v106
	global_load_dwordx4 v[114:117], v0, s[72:73] offset:144
	global_load_dwordx4 v[118:121], v0, s[72:73] offset:128
	global_load_dwordx4 v[106:109], v0, s[72:73] offset:272
	global_load_dwordx4 v[110:113], v0, s[72:73] offset:256
	s_mov_b32 s59, 0x28990800
	s_cselect_b32 s59, s59, 0x21910800
	v_mul_f32_e32 v197, 0x45800000, v196
	v_cndmask_b32_e32 v196, v196, v197, vcc
	v_pk_mul_f32 v[200:201], v[158:159], v[196:197] op_sel_hi:[1,0]
	v_pk_mul_f32 v[210:211], v[154:155], v[196:197] op_sel_hi:[1,0]
	v_mul_f32_e32 v154, v201, v201
	v_pk_mul_f32 v[198:199], v[160:161], v[196:197] op_sel_hi:[1,0]
	v_pk_mul_f32 v[202:203], v[156:157], v[196:197] op_sel_hi:[1,0]
	v_mul_f32_e32 v156, v166, v166
	v_pk_fma_f32 v[154:155], v[200:201], v[200:201], v[154:155] op_sel_hi:[1,1,0]
	v_mul_f32_e32 v158, v167, v167
	v_mov_b32_e32 v155, v156
	v_mul_f32_e32 v156, v199, v199
	v_pk_fma_f32 v[156:157], v[198:199], v[198:199], v[156:157] op_sel_hi:[1,1,0]
	v_mul_f32_e32 v159, v168, v168
	v_mov_b32_e32 v157, v158
	v_pk_add_f32 v[154:155], v[154:155], v[156:157]
	v_mul_f32_e32 v156, v211, v211
	v_pk_fma_f32 v[156:157], v[210:211], v[210:211], v[156:157] op_sel_hi:[1,1,0]
	v_mul_f32_e32 v158, v203, v203
	v_mul_f32_e32 v160, v169, v169
	v_mov_b32_e32 v157, v159
	v_pk_fma_f32 v[158:159], v[202:203], v[202:203], v[158:159] op_sel_hi:[1,1,0]
	v_pk_mul_f32 v[176:177], v[176:177], v[196:197] op_sel_hi:[1,0]
	v_mov_b32_e32 v159, v160
	v_pk_mul_f32 v[212:213], v[174:175], v[196:197] op_sel_hi:[1,0]
	v_pk_add_f32 v[156:157], v[156:157], v[158:159]
	v_mul_f32_e32 v158, v177, v177
	v_pk_add_f32 v[154:155], v[154:155], v[156:157]
	v_mul_f32_e32 v156, v213, v213
	v_pk_mul_f32 v[214:215], v[172:173], v[196:197] op_sel_hi:[1,0]
	v_pk_mul_f32 v[196:197], v[170:171], v[196:197] op_sel_hi:[1,0]
	v_mul_f32_e32 v161, v162, v162
	v_mul_f32_e32 v170, v163, v163
	v_pk_fma_f32 v[156:157], v[212:213], v[212:213], v[156:157] op_sel_hi:[1,1,0]
	v_pk_fma_f32 v[158:159], v[176:177], v[176:177], v[158:159] op_sel_hi:[1,1,0]
	v_mov_b32_e32 v157, v161
	v_mov_b32_e32 v159, v170
	v_pk_add_f32 v[156:157], v[156:157], v[158:159]
	v_mul_f32_e32 v158, v197, v197
	v_mul_f32_e32 v160, v215, v215
	v_mul_f32_e32 v171, v164, v164
	v_mul_f32_e32 v172, v165, v165
	v_pk_fma_f32 v[158:159], v[196:197], v[196:197], v[158:159] op_sel_hi:[1,1,0]
	v_pk_fma_f32 v[160:161], v[214:215], v[214:215], v[160:161] op_sel_hi:[1,1,0]
	v_mov_b32_e32 v159, v171
	v_mov_b32_e32 v161, v172
	v_pk_add_f32 v[158:159], v[158:159], v[160:161]
	s_add_u32 s64, s74, s59
	v_pk_add_f32 v[156:157], v[156:157], v[158:159]
	v_mul_lo_u32 v172, v204, s21
	v_pk_add_f32 v[154:155], v[154:155], v[156:157]
	v_xor_b32_e32 v156, 2, v238
	v_add_f32_e32 v154, v154, v155
	ds_bpermute_b32 v155, v205, v154
	v_cmp_lt_i32_e32 vcc, v156, v195
	s_addc_u32 s65, s75, 0
	v_lshl_add_u64 v[158:159], v[192:193], 0, v[0:1]
	v_cndmask_b32_e32 v156, v238, v156, vcc
	v_lshlrev_b32_e32 v174, 2, v156
	s_waitcnt lgkmcnt(0)
	v_add_f32_e32 v154, v154, v155
	ds_bpermute_b32 v155, v174, v154
	v_mov_b32_e32 v195, v1
	v_fmamk_f32 v173, v191, 0x3b800000, v233
	v_lshl_add_u64 v[216:217], v[194:195], 1, s[64:65]
	v_mul_f32_e32 v175, 0x4b800000, v173
	s_waitcnt lgkmcnt(0)
	v_add_f32_e32 v154, v154, v155
	v_fmamk_f32 v154, v154, 0x3c2aaaab, v233
	v_mul_f32_e32 v155, 0x4b800000, v154
	v_cmp_gt_f32_e32 vcc, s25, v154
	v_mul_f32_e32 v191, v153, v153
	s_addk_i32 s57, 0x80
	v_cndmask_b32_e32 v154, v154, v155, vcc
	v_rsq_f32_e32 v170, v154
	global_load_dwordx4 v[154:157], v[158:159], off offset:16
	s_nop 0
	global_load_dwordx4 v[158:161], v[158:159], off
	s_mov_b64 s[74:75], -1
	v_mul_f32_e32 v171, 0x45800000, v170
	v_cndmask_b32_e32 v204, v170, v171, vcc
	v_pk_mul_f32 v[170:171], v[134:135], v[204:205] op_sel_hi:[1,0]
	v_pk_mul_f32 v[192:193], v[136:137], v[204:205] op_sel_hi:[1,0]
	v_pk_mul_f32 v[170:171], v[200:201], v[170:171]
	v_pk_mul_f32 v[194:195], v[198:199], v[192:193]
	v_pk_mul_f32 v[192:193], v[122:123], v[204:205] op_sel_hi:[1,0]
	v_pk_mul_f32 v[198:199], v[124:125], v[204:205] op_sel_hi:[1,0]
	v_cmp_gt_f32_e32 vcc, s25, v173
	v_pk_mul_f32 v[198:199], v[202:203], v[198:199]
	v_pk_mul_f32 v[200:201], v[210:211], v[192:193]
	v_cvt_pk_bf16_f32 v192, v170, v171
	v_lshlrev_b32_e32 v170, 1, v209
	v_mov_b32_e32 v171, v1
	v_cndmask_b32_e32 v173, v173, v175, vcc
	v_cvt_pk_bf16_f32 v193, v194, v195
	v_cvt_pk_bf16_f32 v194, v200, v201
	v_cvt_pk_bf16_f32 v195, v198, v199
	v_lshl_add_u64 v[198:199], v[216:217], 0, v[170:171]
	v_rsq_f32_e32 v173, v173
	global_store_dwordx4 v[198:199], v[192:195], off
	s_waitcnt vmcnt(6)
	v_pk_mul_f32 v[200:201], v[116:117], v[204:205] op_sel_hi:[1,0]
	v_mul_f32_e32 v202, v146, v146
	s_waitcnt vmcnt(5)
; DEVI u32x4 pack8(const f32x4 a, const f32x4 b) { u32x4 w; w.x = cvtpk(a[0], a[1]); w.y = cvtpk(a[2], a[3]); w.z = cvtpk(b[0], b[1]); w.w = cvtpk(b[2], b[3]); return w; }
; DEVI float ss4(const f32x4 a) { return (a[0] * a[0] + a[1] * a[1]) + (a[2] * a[2] + a[3] * a[3]); }
; DEVI float red_fq(float s) { s += __shfl_xor(s, 16); s += __shfl_xor(s, 32); return s; }
;     DEVI void operator()(AccRef acc, const Unit& u, int wr, int wc, int fr, int fq) const {
;     ...
;             for (int m = 0; m < 4; ++m) {
;                 const float r = cache ? 1.f : rsqrtf(rr[m] * (1.f / 256.f) + EPSF);
;                 const f32x4 v00 = acc[ai][0][m][0] * r, v01 = acc[ai][0][m][1] * r, v10 = acc[ai][1][m][0] * r, v11 = acc[ai][1][m][1] * r;
;                 const float s = red_fq(((ss4(v00) + ss4(v01)) + (ss4(v10) + ss4(v11))) + (ss4(k0[m]) + ss4(k1[m])));
;                 const float sc = rsqrtf(s * (1.f / 96.f) + EPSF);
;                 bf16_t* kd = kbase + ko[m];
;                 *(u32x4*)(kd + 8 * fq) = pack8(v00 * (g0 * sc), v01 * (g1 * sc));
;                 *(u32x4*)(kd + 32 + 8 * fq) = pack8(v10 * (g2 * sc), v11 * (g3 * sc));
;                 *(u32x4*)(kd + 64 + 8 * fq) = pack8(k0[m] * (g4 * sc), k1[m] * (g5 * sc));
	v_pk_mul_f32 v[194:195], v[120:121], v[204:205] op_sel_hi:[1,0]
	v_pk_mul_f32 v[192:193], v[118:119], v[204:205] op_sel_hi:[1,0]
	v_pk_mul_f32 v[176:177], v[176:177], v[194:195]
	v_pk_mul_f32 v[194:195], v[114:115], v[204:205] op_sel_hi:[1,0]
	v_pk_mul_f32 v[192:193], v[212:213], v[192:193]
	v_pk_mul_f32 v[200:201], v[214:215], v[200:201]
	v_pk_mul_f32 v[194:195], v[196:197], v[194:195]
	v_cvt_pk_bf16_f32 v192, v192, v193
	v_cvt_pk_bf16_f32 v193, v176, v177
	v_cvt_pk_bf16_f32 v194, v194, v195
	v_cvt_pk_bf16_f32 v195, v200, v201
	v_mul_f32_e32 v175, 0x45800000, v173
	global_store_dwordx4 v[198:199], v[192:195], off offset:64
	v_mul_f32_e32 v203, v147, v147
	v_mul_f32_e32 v209, v148, v148
	v_cndmask_b32_e32 v194, v173, v175, vcc
	v_pk_mul_f32 v[130:131], v[130:131], v[194:195] op_sel_hi:[1,0]
	v_pk_mul_f32 v[200:201], v[126:127], v[194:195] op_sel_hi:[1,0]
	v_mul_f32_e32 v126, v131, v131
	v_pk_mul_f32 v[132:133], v[132:133], v[194:195] op_sel_hi:[1,0]
	v_pk_mul_f32 v[196:197], v[128:129], v[194:195] op_sel_hi:[1,0]
	v_mul_f32_e32 v128, v150, v150
	v_pk_fma_f32 v[126:127], v[130:131], v[130:131], v[126:127] op_sel_hi:[1,1,0]
	v_mul_f32_e32 v173, v151, v151
	v_mov_b32_e32 v127, v128
	v_mul_f32_e32 v128, v133, v133
	v_pk_fma_f32 v[128:129], v[132:133], v[132:133], v[128:129] op_sel_hi:[1,1,0]
	v_pk_mul_f32 v[144:145], v[144:145], v[194:195] op_sel_hi:[1,0]
	v_mov_b32_e32 v129, v173
	v_pk_mul_f32 v[142:143], v[142:143], v[194:195] op_sel_hi:[1,0]
	v_pk_mul_f32 v[140:141], v[140:141], v[194:195] op_sel_hi:[1,0]
	v_pk_mul_f32 v[138:139], v[138:139], v[194:195] op_sel_hi:[1,0]
	v_pk_add_f32 v[126:127], v[126:127], v[128:129]
	v_mul_f32_e32 v128, v201, v201
	v_mul_f32_e32 v194, v197, v197
	v_mul_f32_e32 v175, v152, v152
	v_pk_fma_f32 v[128:129], v[200:201], v[200:201], v[128:129] op_sel_hi:[1,1,0]
	v_pk_fma_f32 v[194:195], v[196:197], v[196:197], v[194:195] op_sel_hi:[1,1,0]
	v_mov_b32_e32 v129, v175
	v_mov_b32_e32 v195, v191
	v_pk_add_f32 v[128:129], v[128:129], v[194:195]
	v_mul_f32_e32 v194, v145, v145
	v_pk_add_f32 v[126:127], v[126:127], v[128:129]
	v_mul_f32_e32 v128, v143, v143
	v_pk_fma_f32 v[128:129], v[142:143], v[142:143], v[128:129] op_sel_hi:[1,1,0]
	v_pk_fma_f32 v[194:195], v[144:145], v[144:145], v[194:195] op_sel_hi:[1,1,0]
	v_mov_b32_e32 v129, v202
	v_mov_b32_e32 v195, v203
	v_pk_add_f32 v[128:129], v[128:129], v[194:195]
	v_mul_f32_e32 v194, v139, v139
	v_mul_f32_e32 v202, v141, v141
	v_mul_f32_e32 v210, v149, v149
	v_pk_fma_f32 v[194:195], v[138:139], v[138:139], v[194:195] op_sel_hi:[1,1,0]
	v_pk_fma_f32 v[202:203], v[140:141], v[140:141], v[202:203] op_sel_hi:[1,1,0]
	v_mov_b32_e32 v195, v209
	v_mov_b32_e32 v203, v210
	v_pk_add_f32 v[194:195], v[194:195], v[202:203]
	s_waitcnt vmcnt(4)
	v_pk_mul_f32 v[176:177], v[110:111], v[204:205] op_sel_hi:[1,0]
	v_pk_add_f32 v[128:129], v[128:129], v[194:195]
	v_pk_mul_f32 v[192:193], v[112:113], v[204:205] op_sel_hi:[1,0]
	v_pk_add_f32 v[126:127], v[126:127], v[128:129]
	v_pk_mul_f32 v[128:129], v[168:169], v[192:193]
	v_add_f32_e32 v173, v126, v127
	ds_bpermute_b32 v175, v205, v173
	v_pk_mul_f32 v[126:127], v[166:167], v[176:177]
	v_pk_mul_f32 v[166:167], v[106:107], v[204:205] op_sel_hi:[1,0]
	v_cvt_pk_bf16_f32 v126, v126, v127
	v_cvt_pk_bf16_f32 v127, v128, v129
	s_waitcnt lgkmcnt(0)
	v_add_f32_e32 v173, v173, v175
	ds_bpermute_b32 v175, v174, v173
	v_pk_mul_f32 v[162:163], v[162:163], v[166:167]
	v_pk_mul_f32 v[168:169], v[108:109], v[204:205] op_sel_hi:[1,0]
	v_mov_b32_e32 v191, v1
	v_pk_mul_f32 v[164:165], v[164:165], v[168:169]
	s_waitcnt lgkmcnt(0)
	v_add_f32_e32 v128, v173, v175
	v_fmamk_f32 v128, v128, 0x3c2aaaab, v233
	v_mul_f32_e32 v129, 0x4b800000, v128
	v_cmp_gt_f32_e32 vcc, s25, v128
	v_mov_b32_e32 v173, v1
	s_nop 0
	v_cndmask_b32_e32 v128, v128, v129, vcc
	v_rsq_f32_e32 v166, v128
	v_cvt_pk_bf16_f32 v128, v162, v163
	v_cvt_pk_bf16_f32 v129, v164, v165
	global_store_dwordx4 v[198:199], v[126:129], off offset:128
	v_lshl_add_u64 v[164:165], v[190:191], 1, s[64:65]
	s_nop 0
	v_mul_f32_e32 v126, 0x45800000, v166
	v_cndmask_b32_e32 v162, v166, v126, vcc
	v_pk_mul_f32 v[126:127], v[134:135], v[162:163] op_sel_hi:[1,0]
	v_pk_mul_f32 v[128:129], v[136:137], v[162:163] op_sel_hi:[1,0]
	v_pk_mul_f32 v[126:127], v[130:131], v[126:127]
	v_pk_mul_f32 v[128:129], v[132:133], v[128:129]
	v_pk_mul_f32 v[130:131], v[122:123], v[162:163] op_sel_hi:[1,0]
	v_pk_mul_f32 v[132:133], v[124:125], v[162:163] op_sel_hi:[1,0]
	v_pk_mul_f32 v[130:131], v[200:201], v[130:131]
	v_pk_mul_f32 v[132:133], v[196:197], v[132:133]
	v_cvt_pk_bf16_f32 v126, v126, v127
	v_cvt_pk_bf16_f32 v127, v128, v129
	v_cvt_pk_bf16_f32 v128, v130, v131
	v_cvt_pk_bf16_f32 v129, v132, v133
	v_lshl_add_u64 v[130:131], v[164:165], 0, v[170:171]
	global_store_dwordx4 v[130:131], v[126:129], off
	v_pk_mul_f32 v[132:133], v[114:115], v[162:163] op_sel_hi:[1,0]
	s_nop 0
	v_pk_mul_f32 v[126:127], v[118:119], v[162:163] op_sel_hi:[1,0]
	v_pk_mul_f32 v[128:129], v[120:121], v[162:163] op_sel_hi:[1,0]
	v_pk_mul_f32 v[126:127], v[142:143], v[126:127]
	v_pk_mul_f32 v[128:129], v[144:145], v[128:129]
	v_pk_mul_f32 v[132:133], v[138:139], v[132:133]
	v_cvt_pk_bf16_f32 v126, v126, v127
	v_cvt_pk_bf16_f32 v127, v128, v129
	v_cvt_pk_bf16_f32 v128, v132, v133
	v_fmamk_f32 v132, v189, 0x3b800000, v233
	v_mul_f32_e32 v133, 0x4b800000, v132
	v_cmp_gt_f32_e32 vcc, s25, v132
	v_pk_mul_f32 v[142:143], v[116:117], v[162:163] op_sel_hi:[1,0]
	v_mul_f32_e32 v144, v99, v99
	v_cndmask_b32_e32 v132, v132, v133, vcc
	v_rsq_f32_e32 v132, v132
	v_pk_mul_f32 v[140:141], v[140:141], v[142:143]
	v_mul_f32_e32 v142, v105, v105
	v_cvt_pk_bf16_f32 v129, v140, v141
; DEVI u32x4 pack8(const f32x4 a, const f32x4 b) { u32x4 w; w.x = cvtpk(a[0], a[1]); w.y = cvtpk(a[2], a[3]); w.z = cvtpk(b[0], b[1]); w.w = cvtpk(b[2], b[3]); return w; }
; DEVI float ss4(const f32x4 a) { return (a[0] * a[0] + a[1] * a[1]) + (a[2] * a[2] + a[3] * a[3]); }
; DEVI float red_fq(float s) { s += __shfl_xor(s, 16); s += __shfl_xor(s, 32); return s; }
;     DEVI void operator()(AccRef acc, const Unit& u, int wr, int wc, int fr, int fq) const {
;     ...
;             for (int m = 0; m < 4; ++m) {
;                 const float r = cache ? 1.f : rsqrtf(rr[m] * (1.f / 256.f) + EPSF);
;                 const f32x4 v00 = acc[ai][0][m][0] * r, v01 = acc[ai][0][m][1] * r, v10 = acc[ai][1][m][0] * r, v11 = acc[ai][1][m][1] * r;
;                 const float s = red_fq(((ss4(v00) + ss4(v01)) + (ss4(v10) + ss4(v11))) + (ss4(k0[m]) + ss4(k1[m])));
;                 const float sc = rsqrtf(s * (1.f / 96.f) + EPSF);
;                 bf16_t* kd = kbase + ko[m];
;                 *(u32x4*)(kd + 8 * fq) = pack8(v00 * (g0 * sc), v01 * (g1 * sc));
;                 *(u32x4*)(kd + 32 + 8 * fq) = pack8(v10 * (g2 * sc), v11 * (g3 * sc));
;                 *(u32x4*)(kd + 64 + 8 * fq) = pack8(k0[m] * (g4 * sc), k1[m] * (g5 * sc));
	v_mul_f32_e32 v133, 0x45800000, v132
	v_cndmask_b32_e32 v132, v132, v133, vcc
	v_pk_mul_f32 v[86:87], v[86:87], v[132:133] op_sel_hi:[1,0]
	v_pk_mul_f32 v[140:141], v[82:83], v[132:133] op_sel_hi:[1,0]
	v_mul_f32_e32 v82, v87, v87
	v_pk_mul_f32 v[88:89], v[88:89], v[132:133] op_sel_hi:[1,0]
	v_pk_mul_f32 v[138:139], v[84:85], v[132:133] op_sel_hi:[1,0]
	v_mul_f32_e32 v84, v102, v102
	v_pk_fma_f32 v[82:83], v[86:87], v[86:87], v[82:83] op_sel_hi:[1,1,0]
	v_pk_mul_f32 v[96:97], v[96:97], v[132:133] op_sel_hi:[1,0]
	v_mov_b32_e32 v83, v84
	v_mul_f32_e32 v84, v89, v89
	v_pk_mul_f32 v[94:95], v[94:95], v[132:133] op_sel_hi:[1,0]
	v_pk_mul_f32 v[92:93], v[92:93], v[132:133] op_sel_hi:[1,0]
	v_pk_mul_f32 v[90:91], v[90:91], v[132:133] op_sel_hi:[1,0]
	v_mul_f32_e32 v132, v103, v103
	v_pk_fma_f32 v[84:85], v[88:89], v[88:89], v[84:85] op_sel_hi:[1,1,0]
	v_mul_f32_e32 v133, v104, v104
	v_mov_b32_e32 v85, v132
	v_pk_add_f32 v[82:83], v[82:83], v[84:85]
	v_mul_f32_e32 v84, v141, v141
	v_pk_fma_f32 v[84:85], v[140:141], v[140:141], v[84:85] op_sel_hi:[1,1,0]
	v_mul_f32_e32 v132, v139, v139
	v_mov_b32_e32 v85, v133
	v_pk_fma_f32 v[132:133], v[138:139], v[138:139], v[132:133] op_sel_hi:[1,1,0]
	v_mul_f32_e32 v143, v98, v98
	v_mov_b32_e32 v133, v142
	v_pk_add_f32 v[84:85], v[84:85], v[132:133]
	v_mul_f32_e32 v132, v97, v97
	v_pk_add_f32 v[82:83], v[82:83], v[84:85]
	v_mul_f32_e32 v84, v95, v95
	v_pk_fma_f32 v[84:85], v[94:95], v[94:95], v[84:85] op_sel_hi:[1,1,0]
	v_pk_fma_f32 v[132:133], v[96:97], v[96:97], v[132:133] op_sel_hi:[1,1,0]
	v_mov_b32_e32 v85, v143
	v_mov_b32_e32 v133, v144
	v_pk_add_f32 v[84:85], v[84:85], v[132:133]
	v_mul_f32_e32 v132, v91, v91
	v_mul_f32_e32 v142, v93, v93
	global_store_dwordx4 v[130:131], v[126:129], off offset:64
	v_mul_f32_e32 v145, v100, v100
	v_pk_fma_f32 v[132:133], v[90:91], v[90:91], v[132:133] op_sel_hi:[1,1,0]
	v_pk_mul_f32 v[126:127], v[110:111], v[162:163] op_sel_hi:[1,0]
	v_pk_mul_f32 v[128:129], v[112:113], v[162:163] op_sel_hi:[1,0]
	v_mul_f32_e32 v163, v101, v101
	v_pk_fma_f32 v[142:143], v[92:93], v[92:93], v[142:143] op_sel_hi:[1,1,0]
	v_mov_b32_e32 v133, v145
	v_mov_b32_e32 v143, v163
	v_pk_add_f32 v[132:133], v[132:133], v[142:143]
	v_mov_b32_e32 v189, v1
	v_pk_add_f32 v[84:85], v[84:85], v[132:133]
	s_nop 0
	v_pk_add_f32 v[82:83], v[82:83], v[84:85]
	v_pk_mul_f32 v[84:85], v[152:153], v[128:129]
	v_add_f32_e32 v132, v82, v83
	ds_bpermute_b32 v133, v205, v132
	v_pk_mul_f32 v[82:83], v[150:151], v[126:127]
	v_pk_mul_f32 v[126:127], v[106:107], v[162:163] op_sel_hi:[1,0]
	v_cvt_pk_bf16_f32 v82, v82, v83
	v_cvt_pk_bf16_f32 v83, v84, v85
	s_waitcnt lgkmcnt(0)
	v_add_f32_e32 v132, v132, v133
	ds_bpermute_b32 v133, v174, v132
	v_pk_mul_f32 v[128:129], v[108:109], v[162:163] op_sel_hi:[1,0]
	v_pk_mul_f32 v[126:127], v[146:147], v[126:127]
	v_pk_mul_f32 v[128:129], v[148:149], v[128:129]
	s_waitcnt lgkmcnt(0)
	v_add_f32_e32 v84, v132, v133
	v_fmamk_f32 v84, v84, 0x3c2aaaab, v233
	v_mul_f32_e32 v85, 0x4b800000, v84
	v_cmp_gt_f32_e32 vcc, s25, v84
	s_nop 1
	v_cndmask_b32_e32 v84, v84, v85, vcc
	v_rsq_f32_e32 v132, v84
	v_cvt_pk_bf16_f32 v84, v126, v127
	v_cvt_pk_bf16_f32 v85, v128, v129
	global_store_dwordx4 v[130:131], v[82:85], off offset:128
	v_lshl_add_u64 v[128:129], v[188:189], 1, s[64:65]
	s_nop 0
	v_mul_f32_e32 v82, 0x45800000, v132
	v_cndmask_b32_e32 v126, v132, v82, vcc
	v_pk_mul_f32 v[82:83], v[134:135], v[126:127] op_sel_hi:[1,0]
	v_pk_mul_f32 v[84:85], v[136:137], v[126:127] op_sel_hi:[1,0]
	v_pk_mul_f32 v[82:83], v[86:87], v[82:83]
	v_pk_mul_f32 v[84:85], v[88:89], v[84:85]
	v_pk_mul_f32 v[86:87], v[122:123], v[126:127] op_sel_hi:[1,0]
	v_pk_mul_f32 v[88:89], v[124:125], v[126:127] op_sel_hi:[1,0]
	v_pk_mul_f32 v[86:87], v[140:141], v[86:87]
	v_pk_mul_f32 v[88:89], v[138:139], v[88:89]
	v_cvt_pk_bf16_f32 v82, v82, v83
	v_cvt_pk_bf16_f32 v83, v84, v85
	v_cvt_pk_bf16_f32 v84, v86, v87
	v_cvt_pk_bf16_f32 v85, v88, v89
	v_lshl_add_u64 v[86:87], v[128:129], 0, v[170:171]
	global_store_dwordx4 v[86:87], v[82:85], off
	v_pk_mul_f32 v[88:89], v[114:115], v[126:127] op_sel_hi:[1,0]
	s_nop 0
	v_pk_mul_f32 v[82:83], v[118:119], v[126:127] op_sel_hi:[1,0]
	v_pk_mul_f32 v[84:85], v[120:121], v[126:127] op_sel_hi:[1,0]
	v_pk_mul_f32 v[82:83], v[94:95], v[82:83]
	v_pk_mul_f32 v[84:85], v[96:97], v[84:85]
	v_pk_mul_f32 v[88:89], v[90:91], v[88:89]
	v_cvt_pk_bf16_f32 v82, v82, v83
	v_cvt_pk_bf16_f32 v83, v84, v85
	v_cvt_pk_bf16_f32 v84, v88, v89
	v_fmamk_f32 v88, v208, 0x3b800000, v233
	v_mul_f32_e32 v89, 0x4b800000, v88
	v_cmp_gt_f32_e32 vcc, s25, v88
	v_pk_mul_f32 v[94:95], v[116:117], v[126:127] op_sel_hi:[1,0]
	s_waitcnt vmcnt(8)
	v_mul_f32_e32 v96, v155, v155
	v_cndmask_b32_e32 v88, v88, v89, vcc
	v_rsq_f32_e32 v88, v88
	v_pk_mul_f32 v[92:93], v[92:93], v[94:95]
	s_waitcnt vmcnt(7)
; DEVI u32x4 pack8(const f32x4 a, const f32x4 b) { u32x4 w; w.x = cvtpk(a[0], a[1]); w.y = cvtpk(a[2], a[3]); w.z = cvtpk(b[0], b[1]); w.w = cvtpk(b[2], b[3]); return w; }
; DEVI float ss4(const f32x4 a) { return (a[0] * a[0] + a[1] * a[1]) + (a[2] * a[2] + a[3] * a[3]); }
; DEVI float red_fq(float s) { s += __shfl_xor(s, 16); s += __shfl_xor(s, 32); return s; }
;     DEVI void operator()(AccRef acc, const Unit& u, int wr, int wc, int fr, int fq) const {
;     ...
; #pragma unroll
;             for (int m = 0; m < 4; ++m) {
;                 const int row = ROWOF(u);
;                 const float* krp;
;                 if (cache) { krp = krc + (size_t)row * 32; ko[m] = ((unsigned)((row >> 12) * 8 + hd) * KSL + (row & 4095)) * 96u; rr[m] = 1.f; }
;                 else {
;                     rr[m] = ssq_zkv[row];
;                     if (!samp) { krp = krc + OUT_KRP + ((size_t)l * MP + row) * 32; ko[m] = ((unsigned)((row >> 12) * 8 + hd) * 4096u + (row & 4095)) * 96u; }
;                     else { const int rw = row - MP; krp = krc + OUT_KRS + ((size_t)l * MS + rw) * 32; ko[m] = ((unsigned)((rw >> 4) * 8 + hd) * KSL + 4096u + (rw & 15)) * 96u; }
;     ...
;             for (int m = 0; m < 4; ++m) {
;                 const float r = cache ? 1.f : rsqrtf(rr[m] * (1.f / 256.f) + EPSF);
;                 const f32x4 v00 = acc[ai][0][m][0] * r, v01 = acc[ai][0][m][1] * r, v10 = acc[ai][1][m][0] * r, v11 = acc[ai][1][m][1] * r;
;                 const float s = red_fq(((ss4(v00) + ss4(v01)) + (ss4(v10) + ss4(v11))) + (ss4(k0[m]) + ss4(k1[m])));
;                 const float sc = rsqrtf(s * (1.f / 96.f) + EPSF);
;                 bf16_t* kd = kbase + ko[m];
;                 *(u32x4*)(kd + 8 * fq) = pack8(v00 * (g0 * sc), v01 * (g1 * sc));
;                 *(u32x4*)(kd + 32 + 8 * fq) = pack8(v10 * (g2 * sc), v11 * (g3 * sc));
;                 *(u32x4*)(kd + 64 + 8 * fq) = pack8(k0[m] * (g4 * sc), k1[m] * (g5 * sc));
	v_mul_f32_e32 v94, v161, v161
	v_cvt_pk_bf16_f32 v85, v92, v93
	v_mul_f32_e32 v89, 0x45800000, v88
	v_cndmask_b32_e32 v88, v88, v89, vcc
	v_pk_mul_f32 v[70:71], v[70:71], v[88:89] op_sel_hi:[1,0]
	v_pk_mul_f32 v[92:93], v[66:67], v[88:89] op_sel_hi:[1,0]
	v_mul_f32_e32 v66, v71, v71
	v_pk_mul_f32 v[72:73], v[72:73], v[88:89] op_sel_hi:[1,0]
	v_pk_mul_f32 v[90:91], v[68:69], v[88:89] op_sel_hi:[1,0]
	v_mul_f32_e32 v68, v158, v158
	v_pk_fma_f32 v[66:67], v[70:71], v[70:71], v[66:67] op_sel_hi:[1,1,0]
	v_pk_mul_f32 v[80:81], v[80:81], v[88:89] op_sel_hi:[1,0]
	v_mov_b32_e32 v67, v68
	v_mul_f32_e32 v68, v73, v73
	v_pk_mul_f32 v[78:79], v[78:79], v[88:89] op_sel_hi:[1,0]
	v_pk_mul_f32 v[76:77], v[76:77], v[88:89] op_sel_hi:[1,0]
	v_pk_mul_f32 v[74:75], v[74:75], v[88:89] op_sel_hi:[1,0]
	v_mul_f32_e32 v88, v159, v159
	v_pk_fma_f32 v[68:69], v[72:73], v[72:73], v[68:69] op_sel_hi:[1,1,0]
	v_mul_f32_e32 v89, v160, v160
	v_mov_b32_e32 v69, v88
	v_pk_add_f32 v[66:67], v[66:67], v[68:69]
	v_mul_f32_e32 v68, v93, v93
	v_pk_fma_f32 v[68:69], v[92:93], v[92:93], v[68:69] op_sel_hi:[1,1,0]
	v_mul_f32_e32 v88, v91, v91
	v_mov_b32_e32 v69, v89
	v_pk_fma_f32 v[88:89], v[90:91], v[90:91], v[88:89] op_sel_hi:[1,1,0]
	v_mul_f32_e32 v95, v154, v154
	v_mov_b32_e32 v89, v94
	v_pk_add_f32 v[68:69], v[68:69], v[88:89]
	v_mul_f32_e32 v88, v81, v81
	v_pk_add_f32 v[66:67], v[66:67], v[68:69]
	v_mul_f32_e32 v68, v79, v79
	v_pk_fma_f32 v[68:69], v[78:79], v[78:79], v[68:69] op_sel_hi:[1,1,0]
	v_pk_fma_f32 v[88:89], v[80:81], v[80:81], v[88:89] op_sel_hi:[1,1,0]
	v_mov_b32_e32 v69, v95
	v_mov_b32_e32 v89, v96
	v_pk_add_f32 v[68:69], v[68:69], v[88:89]
	v_mul_f32_e32 v88, v75, v75
	v_mul_f32_e32 v94, v77, v77
	global_store_dwordx4 v[86:87], v[82:85], off offset:64
	v_mul_f32_e32 v97, v156, v156
	v_pk_fma_f32 v[88:89], v[74:75], v[74:75], v[88:89] op_sel_hi:[1,1,0]
	v_pk_mul_f32 v[82:83], v[110:111], v[126:127] op_sel_hi:[1,0]
	v_pk_mul_f32 v[84:85], v[112:113], v[126:127] op_sel_hi:[1,0]
	v_mul_f32_e32 v127, v157, v157
	v_pk_fma_f32 v[94:95], v[76:77], v[76:77], v[94:95] op_sel_hi:[1,1,0]
	v_mov_b32_e32 v89, v97
	v_mov_b32_e32 v95, v127
	v_pk_add_f32 v[88:89], v[88:89], v[94:95]
	s_nop 0
	v_pk_add_f32 v[68:69], v[68:69], v[88:89]
	s_nop 0
	v_pk_add_f32 v[66:67], v[66:67], v[68:69]
	v_pk_mul_f32 v[68:69], v[104:105], v[84:85]
	v_add_f32_e32 v88, v66, v67
	ds_bpermute_b32 v89, v205, v88
	v_pk_mul_f32 v[66:67], v[102:103], v[82:83]
	v_pk_mul_f32 v[82:83], v[106:107], v[126:127] op_sel_hi:[1,0]
	v_cvt_pk_bf16_f32 v66, v66, v67
	v_cvt_pk_bf16_f32 v67, v68, v69
	s_waitcnt lgkmcnt(0)
	v_add_f32_e32 v88, v88, v89
	ds_bpermute_b32 v89, v174, v88
	v_pk_mul_f32 v[84:85], v[108:109], v[126:127] op_sel_hi:[1,0]
	v_pk_mul_f32 v[82:83], v[98:99], v[82:83]
	v_pk_mul_f32 v[84:85], v[100:101], v[84:85]
	s_waitcnt lgkmcnt(0)
	v_add_f32_e32 v68, v88, v89
	v_fmamk_f32 v68, v68, 0x3c2aaaab, v233
	v_mul_f32_e32 v69, 0x4b800000, v68
	v_cmp_gt_f32_e32 vcc, s25, v68
	s_nop 1
	v_cndmask_b32_e32 v68, v68, v69, vcc
	v_rsq_f32_e32 v88, v68
	v_cvt_pk_bf16_f32 v68, v82, v83
	v_cvt_pk_bf16_f32 v69, v84, v85
	global_store_dwordx4 v[86:87], v[66:69], off offset:128
	v_lshl_add_u64 v[84:85], v[172:173], 1, s[64:65]
	s_nop 0
	v_mul_f32_e32 v66, 0x45800000, v88
	v_cndmask_b32_e32 v82, v88, v66, vcc
	v_pk_mul_f32 v[66:67], v[134:135], v[82:83] op_sel_hi:[1,0]
	v_pk_mul_f32 v[68:69], v[136:137], v[82:83] op_sel_hi:[1,0]
	v_pk_mul_f32 v[66:67], v[70:71], v[66:67]
	v_pk_mul_f32 v[68:69], v[72:73], v[68:69]
	v_pk_mul_f32 v[70:71], v[122:123], v[82:83] op_sel_hi:[1,0]
	v_pk_mul_f32 v[72:73], v[124:125], v[82:83] op_sel_hi:[1,0]
	v_pk_mul_f32 v[70:71], v[92:93], v[70:71]
	v_pk_mul_f32 v[72:73], v[90:91], v[72:73]
	v_cvt_pk_bf16_f32 v66, v66, v67
	v_cvt_pk_bf16_f32 v67, v68, v69
	v_cvt_pk_bf16_f32 v68, v70, v71
	v_cvt_pk_bf16_f32 v69, v72, v73
	v_lshl_add_u64 v[70:71], v[84:85], 0, v[170:171]
	global_store_dwordx4 v[70:71], v[66:69], off
	v_pk_mul_f32 v[72:73], v[114:115], v[82:83] op_sel_hi:[1,0]
	s_and_b64 vcc, exec, s[4:5]
	v_pk_mul_f32 v[66:67], v[118:119], v[82:83] op_sel_hi:[1,0]
	v_pk_mul_f32 v[68:69], v[120:121], v[82:83] op_sel_hi:[1,0]
	v_pk_mul_f32 v[66:67], v[78:79], v[66:67]
	v_pk_mul_f32 v[78:79], v[116:117], v[82:83] op_sel_hi:[1,0]
	v_pk_mul_f32 v[68:69], v[80:81], v[68:69]
	v_pk_mul_f32 v[76:77], v[76:77], v[78:79]
	v_pk_mul_f32 v[72:73], v[74:75], v[72:73]
	v_cvt_pk_bf16_f32 v66, v66, v67
	v_cvt_pk_bf16_f32 v67, v68, v69
	v_cvt_pk_bf16_f32 v68, v72, v73
	v_cvt_pk_bf16_f32 v69, v76, v77
	global_store_dwordx4 v[70:71], v[66:69], off offset:64
	v_pk_mul_f32 v[72:73], v[106:107], v[82:83] op_sel_hi:[1,0]
	v_pk_mul_f32 v[74:75], v[108:109], v[82:83] op_sel_hi:[1,0]
	v_pk_mul_f32 v[66:67], v[110:111], v[82:83] op_sel_hi:[1,0]
	v_pk_mul_f32 v[68:69], v[112:113], v[82:83] op_sel_hi:[1,0]
	v_pk_mul_f32 v[66:67], v[158:159], v[66:67]
	v_pk_mul_f32 v[68:69], v[160:161], v[68:69]
	v_pk_mul_f32 v[74:75], v[156:157], v[74:75]
	v_pk_mul_f32 v[72:73], v[154:155], v[72:73]
	v_cvt_pk_bf16_f32 v66, v66, v67
	v_cvt_pk_bf16_f32 v67, v68, v69
	v_cvt_pk_bf16_f32 v68, v72, v73
	v_cvt_pk_bf16_f32 v69, v74, v75
	v_or_b32_e32 v74, s57, v207
	global_store_dwordx4 v[70:71], v[66:69], off offset:128
	v_ashrrev_i32_e32 v75, 31, v74
	s_lshr_b32 s57, s57, 9
	v_lshl_add_u64 v[66:67], v[74:75], 2, s[66:67]
	global_load_dword v78, v[66:67], off
	s_and_b32 s57, s57, 0xffff8
	s_add_i32 s57, s57, s47
	s_lshl_b32 s57, s57, 12
	s_cbranch_vccnz .LBB0_929
	v_lshlrev_b64 v[66:67], 7, v[74:75]
	v_and_b32_e32 v68, 0xfcf, v74
	v_lshl_add_u64 v[66:67], s[70:71], 0, v[66:67]
	v_or_b32_e32 v112, s57, v68
	s_mov_b64 s[74:75], 0

; #define TID() tid_now(wv)
; DEVI unsigned char* WSP() { return *(unsigned char* const __attribute__((address_space(4)))*)(kargs() + 8 * 22); }
; template <class Epi, class Sched>
; __device__ __forceinline__ void gemm_phase(int wv, LAS unsigned char* lds, const Gemm g, const Sched& S, const Epi& E) {
;     ...
;         { const int t2 = TID(), w2 = __builtin_amdgcn_readfirstlane(t2 >> 6), l2 = t2 & 63; Unit eu = cur; eu.ks = 0; if (g.nNr) { eu.pn = cur.pn % g.nNr; eu.ks = cur.pn / g.nNr; } E(acc, eu, w2 >> 2, w2 & 3, l2 & 15, l2 >> 4); }
;     DEVI void operator()(AccRef acc, const Unit& u, int wr, int wc, int fr, int fq) const {
;         unsigned char* ws = WSP();
;         const float* ssq_zkv = (const float*)(ws + O_SSQZ) + (size_t)(5 + l) * MT;
;         const bool samp = !cache && (u.pn * 256 >= MP);
;         bf16_t* vbase = (bf16_t*)(ws + ((cache || samp) ? O_VTS : O_VTP));
;         const unsigned ld = (cache || samp) ? KSL : 4096;
; #pragma unroll
;         for (int bj = 0; bj < 2; ++bj) {
;             const int tok0 = u.pn * 256 + bj * 128 + wc * 32 + 8 * fq;
;             f32x4 r0 = {1.f, 1.f, 1.f, 1.f}, r1 = r0;
;             unsigned pos;
;             if (!cache) {
;                 const f32x4 s0 = *(const f32x4*)(ssq_zkv + tok0), s1 = *(const f32x4*)(ssq_zkv + tok0 + 4);
; #pragma unroll
;                 for (int j = 0; j < 4; ++j) { r0[j] = rsqrtf(s0[j] * (1.f / 256.f) + EPSF); r1[j] = rsqrtf(s1[j] * (1.f / 256.f) + EPSF); }
;             }
;             if (samp) { const int rr = tok0 - MP; pos = (unsigned)(rr >> 4) * 512u * ld + 4096u + ((rr & 8) ? 4u : 0u); }
;             else pos = (unsigned)(tok0 >> 12) * 512u * ld + (unsigned)((tok0 & 4095) & ~15) + ((tok0 & 8) ? 4u : 0u);
.LBB0_965:
	s_mov_b64 s[6:7], s[0:1]
	v_mbcnt_lo_u32_b32 v0, -1, 0
	v_mbcnt_hi_u32_b32 v0, -1, v0
	v_lshl_or_b32 v0, s33, 6, v0
	v_bfe_u32 v131, v0, 2, 4
	v_and_b32_e32 v130, 3, v0
	v_lshl_add_u32 v130, v130, 4, v131
	v_lshlrev_b32_e32 v130, 2, v130
	ds_bpermute_b32 v2, v130, v2
	ds_bpermute_b32 v3, v130, v3
	ds_bpermute_b32 v4, v130, v4
	ds_bpermute_b32 v5, v130, v5
	ds_bpermute_b32 v6, v130, v6
	ds_bpermute_b32 v7, v130, v7
	ds_bpermute_b32 v8, v130, v8
	ds_bpermute_b32 v9, v130, v9
	s_waitcnt lgkmcnt(7)
	ds_bpermute_b32 v10, v130, v10
	ds_bpermute_b32 v11, v130, v11
	ds_bpermute_b32 v12, v130, v12
	ds_bpermute_b32 v13, v130, v13
	ds_bpermute_b32 v14, v130, v14
	ds_bpermute_b32 v15, v130, v15
	ds_bpermute_b32 v16, v130, v16
	ds_bpermute_b32 v17, v130, v17
	s_waitcnt lgkmcnt(7)
	ds_bpermute_b32 v18, v130, v18
	ds_bpermute_b32 v19, v130, v19
	ds_bpermute_b32 v20, v130, v20
	ds_bpermute_b32 v21, v130, v21
	ds_bpermute_b32 v22, v130, v22
	ds_bpermute_b32 v23, v130, v23
	ds_bpermute_b32 v24, v130, v24
	ds_bpermute_b32 v25, v130, v25
	s_waitcnt lgkmcnt(7)
	ds_bpermute_b32 v26, v130, v26
	ds_bpermute_b32 v27, v130, v27
	ds_bpermute_b32 v28, v130, v28
	ds_bpermute_b32 v29, v130, v29
	ds_bpermute_b32 v30, v130, v30
	ds_bpermute_b32 v31, v130, v31
	ds_bpermute_b32 v32, v130, v32
	ds_bpermute_b32 v33, v130, v33
	s_waitcnt lgkmcnt(7)
	ds_bpermute_b32 v34, v130, v34
	ds_bpermute_b32 v35, v130, v35
	ds_bpermute_b32 v36, v130, v36
	ds_bpermute_b32 v37, v130, v37
	ds_bpermute_b32 v38, v130, v38
	ds_bpermute_b32 v39, v130, v39
	ds_bpermute_b32 v40, v130, v40
	ds_bpermute_b32 v41, v130, v41
	s_waitcnt lgkmcnt(7)
	ds_bpermute_b32 v42, v130, v42
	ds_bpermute_b32 v43, v130, v43
	ds_bpermute_b32 v44, v130, v44
	ds_bpermute_b32 v45, v130, v45
	ds_bpermute_b32 v46, v130, v46
	ds_bpermute_b32 v47, v130, v47
	ds_bpermute_b32 v48, v130, v48
	ds_bpermute_b32 v49, v130, v49
	s_waitcnt lgkmcnt(7)
	ds_bpermute_b32 v50, v130, v50
	ds_bpermute_b32 v51, v130, v51
	ds_bpermute_b32 v52, v130, v52
	ds_bpermute_b32 v53, v130, v53
	ds_bpermute_b32 v54, v130, v54
	ds_bpermute_b32 v55, v130, v55
	ds_bpermute_b32 v56, v130, v56
	ds_bpermute_b32 v57, v130, v57
	s_waitcnt lgkmcnt(7)
	ds_bpermute_b32 v58, v130, v58
	ds_bpermute_b32 v59, v130, v59
	ds_bpermute_b32 v60, v130, v60
	ds_bpermute_b32 v61, v130, v61
	ds_bpermute_b32 v62, v130, v62
	ds_bpermute_b32 v63, v130, v63
	ds_bpermute_b32 v64, v130, v64
	ds_bpermute_b32 v65, v130, v65
	s_waitcnt lgkmcnt(7)
	ds_bpermute_b32 v66, v130, v66
	ds_bpermute_b32 v67, v130, v67
	ds_bpermute_b32 v68, v130, v68
	ds_bpermute_b32 v69, v130, v69
	ds_bpermute_b32 v70, v130, v70
	ds_bpermute_b32 v71, v130, v71
	ds_bpermute_b32 v72, v130, v72
	ds_bpermute_b32 v73, v130, v73
	s_waitcnt lgkmcnt(7)
	ds_bpermute_b32 v74, v130, v74
	ds_bpermute_b32 v75, v130, v75
	ds_bpermute_b32 v76, v130, v76
	ds_bpermute_b32 v77, v130, v77
	ds_bpermute_b32 v78, v130, v78
	ds_bpermute_b32 v79, v130, v79
	ds_bpermute_b32 v80, v130, v80
	ds_bpermute_b32 v81, v130, v81
	s_waitcnt lgkmcnt(7)
	ds_bpermute_b32 v82, v130, v82
	ds_bpermute_b32 v83, v130, v83
	ds_bpermute_b32 v84, v130, v84
	ds_bpermute_b32 v85, v130, v85
	ds_bpermute_b32 v86, v130, v86
	ds_bpermute_b32 v87, v130, v87
	ds_bpermute_b32 v88, v130, v88
	ds_bpermute_b32 v89, v130, v89
	s_waitcnt lgkmcnt(7)
	ds_bpermute_b32 v90, v130, v90
	ds_bpermute_b32 v91, v130, v91
	ds_bpermute_b32 v92, v130, v92
	ds_bpermute_b32 v93, v130, v93
	ds_bpermute_b32 v94, v130, v94
	ds_bpermute_b32 v95, v130, v95
	ds_bpermute_b32 v96, v130, v96
	ds_bpermute_b32 v97, v130, v97
	s_waitcnt lgkmcnt(7)
	ds_bpermute_b32 v98, v130, v98
	ds_bpermute_b32 v99, v130, v99
	ds_bpermute_b32 v100, v130, v100
	ds_bpermute_b32 v101, v130, v101
	ds_bpermute_b32 v102, v130, v102
	ds_bpermute_b32 v103, v130, v103
	ds_bpermute_b32 v104, v130, v104
	ds_bpermute_b32 v105, v130, v105
	s_waitcnt lgkmcnt(7)
	ds_bpermute_b32 v106, v130, v106
	ds_bpermute_b32 v107, v130, v107
	ds_bpermute_b32 v108, v130, v108
	ds_bpermute_b32 v109, v130, v109
	ds_bpermute_b32 v110, v130, v110
	ds_bpermute_b32 v111, v130, v111
	ds_bpermute_b32 v112, v130, v112
	ds_bpermute_b32 v113, v130, v113
	s_waitcnt lgkmcnt(7)
	ds_bpermute_b32 v114, v130, v114
	ds_bpermute_b32 v115, v130, v115
	ds_bpermute_b32 v116, v130, v116
	ds_bpermute_b32 v117, v130, v117
	ds_bpermute_b32 v118, v130, v118
	ds_bpermute_b32 v119, v130, v119
	ds_bpermute_b32 v120, v130, v120
	ds_bpermute_b32 v121, v130, v121
	s_waitcnt lgkmcnt(7)
	ds_bpermute_b32 v122, v130, v122
	ds_bpermute_b32 v123, v130, v123
	ds_bpermute_b32 v124, v130, v124
	ds_bpermute_b32 v125, v130, v125
	ds_bpermute_b32 v126, v130, v126
	ds_bpermute_b32 v127, v130, v127
	ds_bpermute_b32 v128, v130, v128
	ds_bpermute_b32 v129, v130, v129
	s_waitcnt lgkmcnt(0)
	s_load_dwordx2 s[62:63], s[6:7], 0xb0
	v_readfirstlane_b32 s57, v0
	v_lshlrev_b32_e32 v130, 3, v0
	s_waitcnt lgkmcnt(0)
	s_add_u32 s6, s62, s43
	s_addc_u32 s7, s63, 0
	s_add_u32 s8, s6, 0x147800
	s_addc_u32 s9, s7, 0
	s_cmpk_lt_i32 s5, 0x80
	s_cselect_b64 s[6:7], -1, 0
	s_cmpk_gt_i32 s5, 0x7f
	s_cselect_b64 s[64:65], -1, 0
	s_and_b64 s[66:67], s[64:65], exec
	s_cselect_b32 s55, s22, 0x1000
	s_lshr_b32 s67, s57, 1
	s_lshl_b32 s66, s5, 8
	s_and_b32 s67, s67, 0x60
	s_or_b32 s66, s67, s66
	v_and_or_b32 v146, v130, 24, s66
	v_ashrrev_i32_e32 v147, 31, v146
	v_lshl_add_u64 v[134:135], v[146:147], 2, s[8:9]
	global_load_dwordx4 v[130:133], v[134:135], off offset:16
	s_nop 0
	global_load_dwordx4 v[134:137], v[134:135], off
	s_lshl_b32 s5, s5, 5
	s_and_b32 s5, s5, 0xfffffe00
	v_lshlrev_b32_e32 v147, 2, v0
	s_mul_i32 s5, s55, s5
	v_and_b32_e32 v150, 4, v147
	v_or_b32_e32 v147, s5, v150
	s_mov_b64 s[66:67], -1
	s_and_b64 vcc, exec, s[6:7]
	s_cbranch_vccz .LBB0_967
	s_movk_i32 s5, 0xf70
	v_and_or_b32 v151, v146, s5, v147
	s_mov_b64 s[66:67], 0

; DEVI unsigned cvtpk(float lo, float hi) { f32x2_t v = {lo, hi}; bf16x2_t b = __builtin_convertvector(v, bf16x2_t); return __builtin_bit_cast(unsigned, b); }
; #define FENCE() asm volatile("" ::: "memory")
; #define ROWLOOP _Pragma("unroll") for (int ai = 0; ai < 2; ++ai) _Pragma("unroll") for (int m = 0; m < 4; ++m)
;     DEVI void operator()(AccRef acc, const Unit& u, int wr, int wc, int fr, int fq) const {
;     ...
;         for (int bj = 0; bj < 2; ++bj) {
;             const int tok0 = u.pn * 256 + bj * 128 + wc * 32 + 8 * fq;
;             f32x4 r0 = {1.f, 1.f, 1.f, 1.f}, r1 = r0;
;             unsigned pos;
;             if (!cache) {
;                 const f32x4 s0 = *(const f32x4*)(ssq_zkv + tok0), s1 = *(const f32x4*)(ssq_zkv + tok0 + 4);
; #pragma unroll
;                 for (int j = 0; j < 4; ++j) { r0[j] = rsqrtf(s0[j] * (1.f / 256.f) + EPSF); r1[j] = rsqrtf(s1[j] * (1.f / 256.f) + EPSF); }
;             }
;             if (samp) { const int rr = tok0 - MP; pos = (unsigned)(rr >> 4) * 512u * ld + 4096u + ((rr & 8) ? 4u : 0u); }
;             else pos = (unsigned)(tok0 >> 12) * 512u * ld + (unsigned)((tok0 & 4095) & ~15) + ((tok0 & 8) ? 4u : 0u);
;             ROWLOOP {
;                 const int c = ROWOF(u);
;                 const f32x4 a = acc[ai][bj][m][0] * r0, b = acc[ai][bj][m][1] * r1;
;                 bf16_t* d = vbase + (pos + (unsigned)c * ld);
;                 u32x2 w0, w1; w0.x = cvtpk(a[0], a[1]); w0.y = cvtpk(a[2], a[3]); w1.x = cvtpk(b[0], b[1]); w1.y = cvtpk(b[2], b[3]);
;                 *(u32x2*)d = w0; *(u32x2*)(d + 8) = w1;
;                 FENCE();
;             }
.LBB0_969:
	s_and_b64 s[64:65], s[64:65], exec
	s_mov_b32 s5, 0x34c90800
	s_cselect_b32 s5, s5, 0x24910800
	s_add_u32 s62, s62, s5
	s_addc_u32 s63, s63, 0
	s_ashr_i32 s5, s57, 2
	s_lshl_b32 s4, s4, 8
	s_andn2_b32 s5, s5, 63
	s_add_i32 s5, s5, s4
	s_mov_b32 s4, 0x358637bd
	v_mov_b64_e32 v[152:153], s[4:5]
	s_waitcnt vmcnt(0)
	v_pk_fma_f32 v[134:135], v[134:135], s[34:35], v[152:153] op_sel_hi:[1,0,0]
	v_bfe_u32 v0, v0, 2, 4
	v_or_b32_e32 v0, s5, v0
	v_mul_f32_e32 v154, 0x4b800000, v134
	v_cmp_gt_f32_e64 s[4:5], s25, v134
	v_cmp_gt_f32_e32 vcc, s25, v135
	v_pk_fma_f32 v[130:131], v[130:131], s[34:35], v[152:153] op_sel_hi:[1,0,0]
	v_cndmask_b32_e64 v134, v134, v154, s[4:5]
	v_mul_f32_e32 v154, 0x4b800000, v135
	v_cndmask_b32_e32 v135, v135, v154, vcc
	v_rsq_f32_e32 v134, v134
	v_rsq_f32_e32 v135, v135
	v_pk_fma_f32 v[136:137], v[136:137], s[34:35], v[152:153] op_sel_hi:[1,0,0]
	v_pk_fma_f32 v[132:133], v[132:133], s[34:35], v[152:153] op_sel_hi:[1,0,0]
	v_pk_mul_f32 v[154:155], v[134:135], s[24:25] op_sel_hi:[1,0]
	s_nop 0
	v_cndmask_b32_e64 v134, v134, v154, s[4:5]
	v_mul_f32_e32 v154, 0x4b800000, v130
	v_cmp_gt_f32_e64 s[4:5], s25, v130
	v_cndmask_b32_e32 v135, v135, v155, vcc
	v_cmp_gt_f32_e32 vcc, s25, v131
	v_cndmask_b32_e64 v130, v130, v154, s[4:5]
	v_mul_f32_e32 v154, 0x4b800000, v131
	v_cndmask_b32_e32 v131, v131, v154, vcc
	v_rsq_f32_e32 v130, v130
	v_rsq_f32_e32 v131, v131
	v_mul_f32_e32 v152, 0x4b800000, v132
	v_pk_mul_f32 v[126:127], v[126:127], v[134:135]
	v_pk_mul_f32 v[118:119], v[118:119], v[134:135]
	v_pk_mul_f32 v[154:155], v[130:131], s[24:25] op_sel_hi:[1,0]
	v_cvt_pk_bf16_f32 v126, v126, v127
	v_cndmask_b32_e64 v130, v130, v154, s[4:5]
	v_mul_f32_e32 v154, 0x4b800000, v136
	v_cmp_gt_f32_e64 s[4:5], s25, v136
	v_cndmask_b32_e32 v131, v131, v155, vcc
	v_cmp_gt_f32_e32 vcc, s25, v137
	v_cndmask_b32_e64 v136, v136, v154, s[4:5]
	v_mul_f32_e32 v154, 0x4b800000, v137
	v_cndmask_b32_e32 v137, v137, v154, vcc
	v_rsq_f32_e32 v136, v136
	v_rsq_f32_e32 v137, v137
	v_cvt_pk_bf16_f32 v118, v118, v119
	v_pk_mul_f32 v[102:103], v[102:103], v[134:135]
	v_pk_mul_f32 v[86:87], v[86:87], v[134:135]
	v_pk_mul_f32 v[154:155], v[136:137], s[24:25] op_sel_hi:[1,0]
	v_cvt_pk_bf16_f32 v102, v102, v103
	v_cndmask_b32_e64 v136, v136, v154, s[4:5]
	v_cmp_gt_f32_e64 s[4:5], s25, v132
	v_cndmask_b32_e32 v137, v137, v155, vcc
	v_cmp_gt_f32_e32 vcc, s25, v133
	v_cndmask_b32_e64 v132, v132, v152, s[4:5]
	v_mul_f32_e32 v152, 0x4b800000, v133
	v_cndmask_b32_e32 v133, v133, v152, vcc
	v_rsq_f32_e32 v132, v132
	v_rsq_f32_e32 v133, v133
	v_pk_mul_f32 v[128:129], v[128:129], v[136:137]
	v_pk_mul_f32 v[120:121], v[120:121], v[136:137]
	v_cvt_pk_bf16_f32 v127, v128, v129
	v_pk_mul_f32 v[152:153], v[132:133], s[24:25] op_sel_hi:[1,0]
	v_cvt_pk_bf16_f32 v119, v120, v121
	v_cndmask_b32_e32 v133, v133, v153, vcc
	v_cndmask_b32_e64 v132, v132, v152, s[4:5]
	v_pk_mul_f32 v[124:125], v[124:125], v[132:133]
	v_pk_mul_f32 v[152:153], v[122:123], v[130:131]
	v_mul_lo_u32 v122, v0, s55
	s_lshl_b32 s4, s55, 4
	v_add_u32_e32 v0, v151, v122
	v_cvt_pk_bf16_f32 v129, v124, v125
	v_pk_mul_f32 v[116:117], v[116:117], v[132:133]
	v_pk_mul_f32 v[124:125], v[114:115], v[130:131]
	v_add_u32_e32 v114, s4, v122
	v_lshl_add_u64 v[154:155], v[0:1], 1, s[62:63]
	v_add_u32_e32 v0, v151, v114
	v_cvt_pk_bf16_f32 v121, v116, v117
	v_pk_mul_f32 v[104:105], v[104:105], v[136:137]
	v_pk_mul_f32 v[100:101], v[100:101], v[132:133]
	v_pk_mul_f32 v[116:117], v[98:99], v[130:131]
	v_add_u32_e32 v98, s4, v114
	v_cvt_pk_bf16_f32 v128, v152, v153
	global_store_dwordx2 v[154:155], v[126:127], off
	global_store_dwordx2 v[154:155], v[128:129], off offset:16
	v_lshl_add_u64 v[126:127], v[0:1], 1, s[62:63]
	v_add_u32_e32 v0, v151, v98
	v_cvt_pk_bf16_f32 v103, v104, v105
	v_cvt_pk_bf16_f32 v105, v100, v101
	v_pk_mul_f32 v[100:101], v[82:83], v[130:131]
	v_add_u32_e32 v82, s4, v98
	v_cvt_pk_bf16_f32 v120, v124, v125
	global_store_dwordx2 v[126:127], v[118:119], off
	global_store_dwordx2 v[126:127], v[120:121], off offset:16
	v_lshl_add_u64 v[118:119], v[0:1], 1, s[62:63]
	v_pk_mul_f32 v[88:89], v[88:89], v[136:137]
	v_add_u32_e32 v0, v151, v82
	s_mulk_i32 s55, 0x50
	v_cvt_pk_bf16_f32 v104, v116, v117
	global_store_dwordx2 v[118:119], v[102:103], off
	global_store_dwordx2 v[118:119], v[104:105], off offset:16
	v_pk_mul_f32 v[84:85], v[84:85], v[132:133]
	v_lshl_add_u64 v[102:103], v[0:1], 1, s[62:63]
	v_cvt_pk_bf16_f32 v86, v86, v87
	v_cvt_pk_bf16_f32 v87, v88, v89
	v_add_u32_e32 v83, s55, v82
	v_cvt_pk_bf16_f32 v88, v100, v101
	v_cvt_pk_bf16_f32 v89, v84, v85
	global_store_dwordx2 v[102:103], v[86:87], off
	global_store_dwordx2 v[102:103], v[88:89], off offset:16
	v_pk_mul_f32 v[84:85], v[112:113], v[136:137]
	v_pk_mul_f32 v[86:87], v[110:111], v[134:135]
	v_pk_mul_f32 v[100:101], v[106:107], v[130:131]
	v_add_u32_e32 v0, v151, v83
	v_pk_mul_f32 v[88:89], v[108:109], v[132:133]
	v_lshl_add_u64 v[102:103], v[0:1], 1, s[62:63]
	v_cvt_pk_bf16_f32 v86, v86, v87
	v_cvt_pk_bf16_f32 v87, v84, v85
	v_cvt_pk_bf16_f32 v84, v100, v101
	v_cvt_pk_bf16_f32 v85, v88, v89
	global_store_dwordx2 v[102:103], v[86:87], off
	global_store_dwordx2 v[102:103], v[84:85], off offset:16
	v_add_u32_e32 v84, s4, v83
	v_pk_mul_f32 v[86:87], v[96:97], v[136:137]
	v_pk_mul_f32 v[88:89], v[94:95], v[134:135]
	v_pk_mul_f32 v[92:93], v[92:93], v[132:133]
	v_pk_mul_f32 v[90:91], v[90:91], v[130:131]
	v_add_u32_e32 v0, v151, v84
	v_lshl_add_u64 v[94:95], v[0:1], 1, s[62:63]
	v_cvt_pk_bf16_f32 v88, v88, v89
	v_cvt_pk_bf16_f32 v89, v86, v87
	v_cvt_pk_bf16_f32 v86, v90, v91
	v_cvt_pk_bf16_f32 v87, v92, v93
	global_store_dwordx2 v[94:95], v[88:89], off
	global_store_dwordx2 v[94:95], v[86:87], off offset:16
	v_pk_mul_f32 v[86:87], v[76:77], v[132:133]
	v_add_u32_e32 v76, s4, v84
	v_pk_mul_f32 v[80:81], v[80:81], v[136:137]
	v_pk_mul_f32 v[78:79], v[78:79], v[134:135]
	v_pk_mul_f32 v[74:75], v[74:75], v[130:131]
	v_add_u32_e32 v0, v151, v76
	v_add_u32_e32 v77, s4, v76
	v_lshl_add_u64 v[88:89], v[0:1], 1, s[62:63]
	v_cvt_pk_bf16_f32 v78, v78, v79
	v_cvt_pk_bf16_f32 v79, v80, v81
	v_cvt_pk_bf16_f32 v74, v74, v75
	v_cvt_pk_bf16_f32 v75, v86, v87
	v_pk_mul_f32 v[72:73], v[72:73], v[136:137]
	v_pk_mul_f32 v[70:71], v[70:71], v[134:135]
	v_add_u32_e32 v0, v151, v77
	global_store_dwordx2 v[88:89], v[78:79], off
	global_store_dwordx2 v[88:89], v[74:75], off offset:16
	v_pk_mul_f32 v[68:69], v[68:69], v[132:133]
	v_pk_mul_f32 v[66:67], v[66:67], v[130:131]
	v_lshl_add_u64 v[74:75], v[0:1], 1, s[62:63]
	v_cvt_pk_bf16_f32 v70, v70, v71
	v_cvt_pk_bf16_f32 v71, v72, v73
	v_cvt_pk_bf16_f32 v66, v66, v67
	v_cvt_pk_bf16_f32 v67, v68, v69
	global_store_dwordx2 v[74:75], v[70:71], off
	global_store_dwordx2 v[74:75], v[66:67], off offset:16
	v_or_b32_e32 v74, 0x80, v146
	v_ashrrev_i32_e32 v75, 31, v74
	v_lshl_add_u64 v[70:71], v[74:75], 2, s[8:9]
	global_load_dwordx4 v[66:69], v[70:71], off offset:16
	s_nop 0
	global_load_dwordx4 v[70:73], v[70:71], off
	s_mov_b64 s[4:5], -1
	s_andn2_b64 vcc, exec, s[6:7]
	s_cbranch_vccnz .LBB0_971
;     DEVI void operator()(AccRef acc, const Unit& u, int wr, int wc, int fr, int fq) const {
;     ...
;             if (samp) { const int rr = tok0 - MP; pos = (unsigned)(rr >> 4) * 512u * ld + 4096u + ((rr & 8) ? 4u : 0u); }
;             else pos = (unsigned)(tok0 >> 12) * 512u * ld + (unsigned)((tok0 & 4095) & ~15) + ((tok0 & 8) ? 4u : 0u);
	s_movk_i32 s4, 0xff0
	v_and_or_b32 v75, v74, s4, v147
	s_mov_b64 s[4:5], 0

; #define TID() tid_now(wv)
; DEVI unsigned char* WSP() { return *(unsigned char* const __attribute__((address_space(4)))*)(kargs() + 8 * 22); }
; #define ROWLOOP _Pragma("unroll") for (int ai = 0; ai < 2; ++ai) _Pragma("unroll") for (int m = 0; m < 4; ++m)
; template <class Epi, class Sched>
; __device__ __forceinline__ void gemm_phase(int wv, LAS unsigned char* lds, const Gemm g, const Sched& S, const Epi& E) {
;     ...
;         { const int t2 = TID(), w2 = __builtin_amdgcn_readfirstlane(t2 >> 6), l2 = t2 & 63; Unit eu = cur; eu.ks = 0; if (g.nNr) { eu.pn = cur.pn % g.nNr; eu.ks = cur.pn / g.nNr; } E(acc, eu, w2 >> 2, w2 & 3, l2 & 15, l2 >> 4); }
;     DEVI void operator()(AccRef acc, const Unit& u, int wr, int wc, int fr, int fq) const {
;         float* part = (float*)(WSP() + O_ZQ) + (size_t)u.ks * MS * 1024;
;         ROWLOOP {
;             const int row = ROWOF(u);
; #pragma unroll
;             for (int bj = 0; bj < 2; ++bj) {
;                 float* o = part + (unsigned)row * 1024u + u.pn * 256 + bj * 128 + wc * 32 + 8 * fq;
;                 *(f32x4*)o = acc[ai][bj][m][0]; *(f32x4*)(o + 4) = acc[ai][bj][m][1];
;             }
;         }
.LBB0_1775:
	s_mov_b64 s[54:55], s[0:1]
	v_mbcnt_lo_u32_b32 v142, -1, 0
	v_mbcnt_hi_u32_b32 v142, -1, v142
	v_lshl_or_b32 v142, s33, 6, v142
	v_bfe_u32 v141, v142, 2, 4
	v_and_b32_e32 v140, 3, v142
	v_lshl_add_u32 v140, v140, 4, v141
	v_lshlrev_b32_e32 v140, 2, v140
	ds_bpermute_b32 v2, v140, v2
	ds_bpermute_b32 v3, v140, v3
	ds_bpermute_b32 v4, v140, v4
	ds_bpermute_b32 v5, v140, v5
	ds_bpermute_b32 v6, v140, v6
	ds_bpermute_b32 v7, v140, v7
	ds_bpermute_b32 v8, v140, v8
	ds_bpermute_b32 v9, v140, v9
	s_waitcnt lgkmcnt(7)
	ds_bpermute_b32 v10, v140, v10
	ds_bpermute_b32 v11, v140, v11
	ds_bpermute_b32 v12, v140, v12
	ds_bpermute_b32 v13, v140, v13
	ds_bpermute_b32 v14, v140, v14
	ds_bpermute_b32 v15, v140, v15
	ds_bpermute_b32 v16, v140, v16
	ds_bpermute_b32 v17, v140, v17
	s_waitcnt lgkmcnt(7)
	ds_bpermute_b32 v18, v140, v18
	ds_bpermute_b32 v19, v140, v19
	ds_bpermute_b32 v20, v140, v20
	ds_bpermute_b32 v21, v140, v21
	ds_bpermute_b32 v22, v140, v22
	ds_bpermute_b32 v23, v140, v23
	ds_bpermute_b32 v24, v140, v24
	ds_bpermute_b32 v25, v140, v25
	s_waitcnt lgkmcnt(7)
	ds_bpermute_b32 v26, v140, v26
	ds_bpermute_b32 v27, v140, v27
	ds_bpermute_b32 v28, v140, v28
	ds_bpermute_b32 v29, v140, v29
	ds_bpermute_b32 v30, v140, v30
	ds_bpermute_b32 v31, v140, v31
	ds_bpermute_b32 v32, v140, v32
	ds_bpermute_b32 v33, v140, v33
	s_waitcnt lgkmcnt(7)
	ds_bpermute_b32 v34, v140, v34
	ds_bpermute_b32 v35, v140, v35
	ds_bpermute_b32 v36, v140, v36
	ds_bpermute_b32 v37, v140, v37
	ds_bpermute_b32 v38, v140, v38
	ds_bpermute_b32 v39, v140, v39
	ds_bpermute_b32 v40, v140, v40
	ds_bpermute_b32 v41, v140, v41
	s_waitcnt lgkmcnt(7)
	ds_bpermute_b32 v42, v140, v42
	ds_bpermute_b32 v43, v140, v43
	ds_bpermute_b32 v44, v140, v44
	ds_bpermute_b32 v45, v140, v45
	ds_bpermute_b32 v46, v140, v46
	ds_bpermute_b32 v47, v140, v47
	ds_bpermute_b32 v48, v140, v48
	ds_bpermute_b32 v49, v140, v49
	s_waitcnt lgkmcnt(7)
	ds_bpermute_b32 v50, v140, v50
	ds_bpermute_b32 v51, v140, v51
	ds_bpermute_b32 v52, v140, v52
	ds_bpermute_b32 v53, v140, v53
	ds_bpermute_b32 v54, v140, v54
	ds_bpermute_b32 v55, v140, v55
	ds_bpermute_b32 v56, v140, v56
	ds_bpermute_b32 v57, v140, v57
	s_waitcnt lgkmcnt(7)
	ds_bpermute_b32 v58, v140, v58
	ds_bpermute_b32 v59, v140, v59
	ds_bpermute_b32 v60, v140, v60
	ds_bpermute_b32 v61, v140, v61
	ds_bpermute_b32 v62, v140, v62
	ds_bpermute_b32 v63, v140, v63
	ds_bpermute_b32 v64, v140, v64
	ds_bpermute_b32 v65, v140, v65
	s_waitcnt lgkmcnt(7)
	ds_bpermute_b32 v66, v140, v66
	ds_bpermute_b32 v67, v140, v67
	ds_bpermute_b32 v68, v140, v68
	ds_bpermute_b32 v69, v140, v69
	ds_bpermute_b32 v70, v140, v70
	ds_bpermute_b32 v71, v140, v71
	ds_bpermute_b32 v72, v140, v72
	ds_bpermute_b32 v73, v140, v73
	s_waitcnt lgkmcnt(7)
	ds_bpermute_b32 v74, v140, v74
	ds_bpermute_b32 v75, v140, v75
	ds_bpermute_b32 v76, v140, v76
	ds_bpermute_b32 v77, v140, v77
	ds_bpermute_b32 v78, v140, v78
	ds_bpermute_b32 v79, v140, v79
	ds_bpermute_b32 v80, v140, v80
	ds_bpermute_b32 v81, v140, v81
	s_waitcnt lgkmcnt(7)
	ds_bpermute_b32 v82, v140, v82
	ds_bpermute_b32 v83, v140, v83
	ds_bpermute_b32 v84, v140, v84
	ds_bpermute_b32 v85, v140, v85
	ds_bpermute_b32 v86, v140, v86
	ds_bpermute_b32 v87, v140, v87
	ds_bpermute_b32 v88, v140, v88
	ds_bpermute_b32 v89, v140, v89
	s_waitcnt lgkmcnt(7)
	ds_bpermute_b32 v90, v140, v90
	ds_bpermute_b32 v91, v140, v91
	ds_bpermute_b32 v92, v140, v92
	ds_bpermute_b32 v93, v140, v93
	ds_bpermute_b32 v94, v140, v94
	ds_bpermute_b32 v95, v140, v95
	ds_bpermute_b32 v96, v140, v96
	ds_bpermute_b32 v97, v140, v97
	s_waitcnt lgkmcnt(7)
	ds_bpermute_b32 v98, v140, v98
	ds_bpermute_b32 v99, v140, v99
	ds_bpermute_b32 v100, v140, v100
	ds_bpermute_b32 v101, v140, v101
	ds_bpermute_b32 v102, v140, v102
	ds_bpermute_b32 v103, v140, v103
	ds_bpermute_b32 v104, v140, v104
	ds_bpermute_b32 v105, v140, v105
	s_waitcnt lgkmcnt(7)
	ds_bpermute_b32 v106, v140, v106
	ds_bpermute_b32 v107, v140, v107
	ds_bpermute_b32 v108, v140, v108
	ds_bpermute_b32 v109, v140, v109
	ds_bpermute_b32 v110, v140, v110
	ds_bpermute_b32 v111, v140, v111
	ds_bpermute_b32 v112, v140, v112
	ds_bpermute_b32 v113, v140, v113
	s_waitcnt lgkmcnt(7)
	ds_bpermute_b32 v114, v140, v114
	ds_bpermute_b32 v115, v140, v115
	ds_bpermute_b32 v116, v140, v116
	ds_bpermute_b32 v117, v140, v117
	ds_bpermute_b32 v118, v140, v118
	ds_bpermute_b32 v119, v140, v119
	ds_bpermute_b32 v120, v140, v120
	ds_bpermute_b32 v121, v140, v121
	s_waitcnt lgkmcnt(7)
	ds_bpermute_b32 v122, v140, v122
	ds_bpermute_b32 v123, v140, v123
	ds_bpermute_b32 v124, v140, v124
	ds_bpermute_b32 v125, v140, v125
	ds_bpermute_b32 v126, v140, v126
	ds_bpermute_b32 v127, v140, v127
	ds_bpermute_b32 v128, v140, v128
	ds_bpermute_b32 v129, v140, v129
	s_waitcnt lgkmcnt(0)
; DEVI unsigned char* WSP() { return *(unsigned char* const __attribute__((address_space(4)))*)(kargs() + 8 * 22); }
; #define ROWLOOP _Pragma("unroll") for (int ai = 0; ai < 2; ++ai) _Pragma("unroll") for (int m = 0; m < 4; ++m)
;     DEVI void operator()(AccRef acc, const Unit& u, int wr, int wc, int fr, int fq) const {
;         float* part = (float*)(WSP() + O_ZQ) + (size_t)u.ks * MS * 1024;
;         ROWLOOP {
;             const int row = ROWOF(u);
; #pragma unroll
;             for (int bj = 0; bj < 2; ++bj) {
;                 float* o = part + (unsigned)row * 1024u + u.pn * 256 + bj * 128 + wc * 32 + 8 * fq;
;                 *(f32x4*)o = acc[ai][bj][m][0]; *(f32x4*)(o + 4) = acc[ai][bj][m][1];
;             }
;         }
	s_ashr_i32 s52, s12, 31
	s_lshr_b32 s52, s52, 30
	s_load_dwordx2 s[54:55], s[54:55], 0xb0
	s_add_i32 s53, s12, s52
	s_ashr_i32 s52, s53, 2
	s_and_b32 s53, s53, 0xfffffc
	s_sub_i32 s12, s12, s53
	s_ashr_i32 s53, s52, 31
	s_lshl_b64 s[52:53], s[52:53], 21
	s_waitcnt lgkmcnt(0)
	s_add_u32 s52, s54, s52
	s_addc_u32 s53, s55, s53
	v_readfirstlane_b32 s49, v142
	s_add_u32 s52, s52, 0xfcb0800
	s_addc_u32 s53, s53, 0
	s_lshl_b32 s54, s49, 8
	v_lshlrev_b32_e32 v0, 8, v142
	s_and_b32 s54, s54, 0xffff0000
	v_and_b32_e32 v0, 0x3c00, v0
	v_or_b32_e32 v0, s54, v0
	s_lshl_b32 s54, s12, 8
	v_lshl_add_u32 v0, s10, 18, v0
	s_ashr_i32 s55, s54, 31
	v_lshl_add_u64 v[140:141], v[0:1], 2, s[52:53]
	s_lshl_b64 s[54:55], s[54:55], 2
	s_lshl_b32 s10, s49, 1
	v_lshl_add_u64 v[140:141], v[140:141], 0, s[54:55]
	s_and_b32 s12, s10, 0x180
	v_lshlrev_b32_e32 v142, 5, v142
	v_lshl_add_u64 v[140:141], v[140:141], 0, s[12:13]
	v_and_b32_e32 v142, 0x60, v142
	v_mov_b32_e32 v143, v1
	v_lshl_add_u64 v[140:141], v[140:141], 0, v[142:143]
	global_store_dwordx4 v[140:141], v[34:37], off
	global_store_dwordx4 v[140:141], v[38:41], off offset:16
	global_store_dwordx4 v[140:141], v[74:77], off offset:512
	global_store_dwordx4 v[140:141], v[78:81], off offset:528
	v_or_b32_e32 v34, 0x4000, v0
	v_mov_b32_e32 v35, v1
	v_lshl_add_u64 v[34:35], v[34:35], 2, s[52:53]
	v_lshl_add_u64 v[34:35], v[34:35], 0, s[54:55]
	v_lshl_add_u64 v[34:35], v[34:35], 0, s[12:13]
	v_lshl_add_u64 v[34:35], v[34:35], 0, v[142:143]
	global_store_dwordx4 v[34:35], v[18:21], off
	global_store_dwordx4 v[34:35], v[22:25], off offset:16
	global_store_dwordx4 v[34:35], v[58:61], off offset:512
	global_store_dwordx4 v[34:35], v[62:65], off offset:528
	v_or_b32_e32 v18, 0x8000, v0
	v_mov_b32_e32 v19, v1
	v_lshl_add_u64 v[18:19], v[18:19], 2, s[52:53]
	v_lshl_add_u64 v[18:19], v[18:19], 0, s[54:55]
	v_lshl_add_u64 v[18:19], v[18:19], 0, s[12:13]
	v_lshl_add_u64 v[18:19], v[18:19], 0, v[142:143]
	global_store_dwordx4 v[18:19], v[10:13], off
	global_store_dwordx4 v[18:19], v[14:17], off offset:16
	global_store_dwordx4 v[18:19], v[42:45], off offset:512
	global_store_dwordx4 v[18:19], v[46:49], off offset:528
	v_or_b32_e32 v10, 0xc000, v0
	v_mov_b32_e32 v11, v1
	v_lshl_add_u64 v[10:11], v[10:11], 2, s[52:53]
	v_lshl_add_u64 v[10:11], v[10:11], 0, s[54:55]
	v_lshl_add_u64 v[10:11], v[10:11], 0, s[12:13]
	v_lshl_add_u64 v[10:11], v[10:11], 0, v[142:143]
	global_store_dwordx4 v[10:11], v[2:5], off
	global_store_dwordx4 v[10:11], v[6:9], off offset:16
	global_store_dwordx4 v[10:11], v[26:29], off offset:512
	global_store_dwordx4 v[10:11], v[30:33], off offset:528
	v_add_u32_e32 v2, 0x20000, v0
	v_mov_b32_e32 v3, v1
	v_lshl_add_u64 v[2:3], v[2:3], 2, s[52:53]
	v_lshl_add_u64 v[2:3], v[2:3], 0, s[54:55]
	v_lshl_add_u64 v[2:3], v[2:3], 0, s[12:13]
	v_lshl_add_u64 v[2:3], v[2:3], 0, v[142:143]
	global_store_dwordx4 v[2:3], v[98:101], off
	global_store_dwordx4 v[2:3], v[102:105], off offset:16
	global_store_dwordx4 v[2:3], v[122:125], off offset:512
	global_store_dwordx4 v[2:3], v[126:129], off offset:528
	v_add_u32_e32 v2, 0x24000, v0
	v_mov_b32_e32 v3, v1
	v_lshl_add_u64 v[2:3], v[2:3], 2, s[52:53]
	v_lshl_add_u64 v[2:3], v[2:3], 0, s[54:55]
	v_lshl_add_u64 v[2:3], v[2:3], 0, s[12:13]
	v_lshl_add_u64 v[2:3], v[2:3], 0, v[142:143]
	global_store_dwordx4 v[2:3], v[82:85], off
	global_store_dwordx4 v[2:3], v[86:89], off offset:16
	global_store_dwordx4 v[2:3], v[114:117], off offset:512
	global_store_dwordx4 v[2:3], v[118:121], off offset:528
	v_add_u32_e32 v2, 0x28000, v0
	v_mov_b32_e32 v3, v1
	v_lshl_add_u64 v[2:3], v[2:3], 2, s[52:53]
	v_lshl_add_u64 v[2:3], v[2:3], 0, s[54:55]
	v_lshl_add_u64 v[2:3], v[2:3], 0, s[12:13]
	v_lshl_add_u64 v[2:3], v[2:3], 0, v[142:143]
	v_add_u32_e32 v0, 0x2c000, v0
	global_store_dwordx4 v[2:3], v[66:69], off
	global_store_dwordx4 v[2:3], v[70:73], off offset:16
	global_store_dwordx4 v[2:3], v[106:109], off offset:512
	global_store_dwordx4 v[2:3], v[110:113], off offset:528
	v_lshl_add_u64 v[2:3], v[0:1], 2, s[52:53]
	v_lshl_add_u64 v[2:3], v[2:3], 0, s[54:55]
	v_lshl_add_u64 v[2:3], v[2:3], 0, s[12:13]
	v_lshl_add_u64 v[2:3], v[2:3], 0, v[142:143]
	s_and_b64 vcc, exec, s[2:3]
	s_mov_b64 s[2:3], -1
	global_store_dwordx4 v[2:3], v[50:53], off
	global_store_dwordx4 v[2:3], v[54:57], off offset:16
	global_store_dwordx4 v[2:3], v[90:93], off offset:512
	global_store_dwordx4 v[2:3], v[94:97], off offset:528
	s_cbranch_vccnz .LBB0_1762
	s_andn2_b64 vcc, exec, s[6:7]
	s_cbranch_vccnz .LBB0_1761
	s_barrier
	s_branch .LBB0_1761
